# conv passes rebalanced across the 8 waves of a workgroup (waves that also run a retention-total unit take fewer passes)
# baseline (speedup 1.0000x reference)
; DI void conv_unit(int item, const bf16_t* __restrict__ P, bf16_t* __restrict__ Y, const float* __restrict__ cw, const float* __restrict__ cb,
;                   const float* __restrict__ lng, const float* __restrict__ lnb, int lane) {
;     const int tok0 = item * 16;
;     f32x4 w[31];
; #pragma unroll
;     for (int j = 0; j < 31; ++j) w[j] = *(const f32x4*)(cw + j * 256 + 4 * lane);
;     const f32x4 bias = *(const f32x4*)(cb + 4 * lane), g4 = *(const f32x4*)(lng + 4 * lane), b4 = *(const f32x4*)(lnb + 4 * lane);
; #pragma unroll 1
;     for (int ps = 0; ps < 4; ++ps) {
;         const int tok = tok0 + 4 * ps, tl = tok & (SEQ - 1);
;         const bf16_t* src = P + (size_t)tok * PW + P_CV + 4 * lane;
;     ...
;                 const int bid = (G % 8 == 0) ? ((int)blockIdx.x % 8) * (G / 8) + (int)blockIdx.x / 8 : (int)blockIdx.x;
;                 if (wave < 2) { int ln = lane; asm volatile("" : "+v"(ln) :: "memory"); DO_R1(ret1_unit(bid * 2 + wave, T, (float*)(ws + WS_G), ln, lds + wave * 16384)); }
;                 { int ln = lane; asm volatile("" : "+v"(ln) :: "memory"); DO_CV(conv_unit(bid * 8 + wave, P, Y, a.in[6] + l * 31 * 256, a.in[7] + l * 256, a.in[8] + l * 256, a.in[9] + l * 256, ln)); }
.LBB0_702:
	v_mov_b32_e32 v0, v251
	v_readlane_b32 s12, v255, 4
	v_lshlrev_b32_e32 v136, 2, v0
	v_ashrrev_i32_e32 v137, 31, v136
	v_lshlrev_b64 v[132:133], 2, v[136:137]
	v_lshl_add_u64 v[112:113], s[84:85], 0, v[132:133]
	v_add_co_u32_e32 v32, vcc, 0x1000, v112
	s_waitcnt lgkmcnt(0)
	global_load_dwordx4 v[0:3], v[112:113], off
	global_load_dwordx4 v[4:7], v[112:113], off offset:1024
	global_load_dwordx4 v[8:11], v[112:113], off offset:2048
	global_load_dwordx4 v[12:15], v[112:113], off offset:3072
	v_addc_co_u32_e32 v33, vcc, 0, v113, vcc
	v_add_co_u32_e32 v48, vcc, 0x2000, v112
	global_load_dwordx4 v[16:19], v[32:33], off
	global_load_dwordx4 v[20:23], v[32:33], off offset:1024
	global_load_dwordx4 v[24:27], v[32:33], off offset:2048
	global_load_dwordx4 v[28:31], v[32:33], off offset:3072
	v_addc_co_u32_e32 v49, vcc, 0, v113, vcc
	v_add_co_u32_e32 v64, vcc, 0x3000, v112
	global_load_dwordx4 v[32:35], v[48:49], off
	global_load_dwordx4 v[36:39], v[48:49], off offset:1024
	global_load_dwordx4 v[40:43], v[48:49], off offset:2048
	global_load_dwordx4 v[44:47], v[48:49], off offset:3072
	v_addc_co_u32_e32 v65, vcc, 0, v113, vcc
	v_add_co_u32_e32 v80, vcc, 0x4000, v112
	global_load_dwordx4 v[48:51], v[64:65], off
	global_load_dwordx4 v[52:55], v[64:65], off offset:1024
	global_load_dwordx4 v[56:59], v[64:65], off offset:2048
	global_load_dwordx4 v[60:63], v[64:65], off offset:3072
	v_addc_co_u32_e32 v81, vcc, 0, v113, vcc
	v_add_co_u32_e32 v96, vcc, 0x5000, v112
	global_load_dwordx4 v[64:67], v[80:81], off
	global_load_dwordx4 v[68:71], v[80:81], off offset:1024
	global_load_dwordx4 v[72:75], v[80:81], off offset:2048
	global_load_dwordx4 v[76:79], v[80:81], off offset:3072
	v_addc_co_u32_e32 v97, vcc, 0, v113, vcc
	v_add_co_u32_e32 v114, vcc, 0x6000, v112
	global_load_dwordx4 v[80:83], v[96:97], off
	global_load_dwordx4 v[84:87], v[96:97], off offset:1024
	global_load_dwordx4 v[88:91], v[96:97], off offset:2048
	global_load_dwordx4 v[92:95], v[96:97], off offset:3072
	v_addc_co_u32_e32 v115, vcc, 0, v113, vcc
	v_add_co_u32_e32 v120, vcc, 0x7000, v112
	global_load_dwordx4 v[96:99], v[114:115], off
	global_load_dwordx4 v[100:103], v[114:115], off offset:1024
	global_load_dwordx4 v[104:107], v[114:115], off offset:2048
	global_load_dwordx4 v[108:111], v[114:115], off offset:3072
	v_addc_co_u32_e32 v121, vcc, 0, v113, vcc
	v_readlane_b32 s13, v255, 5
	v_readlane_b32 s14, v255, 6
	v_readlane_b32 s15, v255, 7
	global_load_dwordx4 v[112:115], v[120:121], off
	global_load_dwordx4 v[116:119], v[120:121], off offset:1024
	s_nop 0
	global_load_dwordx4 v[120:123], v[120:121], off offset:2048
	v_lshl_add_u64 v[124:125], s[86:87], 0, v[132:133]
	v_lshl_add_u64 v[128:129], s[12:13], 0, v[132:133]
	v_lshl_add_u64 v[132:133], s[14:15], 0, v[132:133]
	global_load_dwordx4 v[124:127], v[124:125], off
	v_mbcnt_lo_u32_b32 v138, -1, 0
	global_load_dwordx4 v[128:131], v[128:129], off
	v_mbcnt_hi_u32_b32 v138, -1, v138
	global_load_dwordx4 v[132:135], v[132:133], off
	v_and_b32_e32 v139, 64, v138
	v_add_u32_e32 v139, 64, v139
	v_xor_b32_e32 v140, 1, v138
	v_cmp_lt_i32_e32 vcc, v140, v139
	s_lshl_b32 s0, s8, 7
	s_and_b32 s101, s96, 3
	s_lshl_b32 s101, s101, 3
	s_mov_b32 s1, 0x70604c38
	s_cmp_lt_u32 s96, 4
	s_cmov_b32 s1, 0x24100800
	s_mov_b32 s100, 0x10101414
	s_cmov_b32 s100, 0x14140808
	s_lshr_b32 s1, s1, s101
	s_lshr_b32 s100, s100, s101
	s_and_b32 s1, s1, 0xff
	s_and_b32 s100, s100, 0xff
	v_cndmask_b32_e32 v140, v138, v140, vcc
	v_lshlrev_b32_e32 v206, 2, v140
	v_xor_b32_e32 v140, 2, v138
	v_cmp_lt_i32_e32 vcc, v140, v139
	s_add_i32 s64, s1, s0
	s_ashr_i32 s65, s64, 31
	v_cndmask_b32_e32 v140, v138, v140, vcc
	v_lshlrev_b32_e32 v207, 2, v140
	v_xor_b32_e32 v140, 4, v138
	v_cmp_lt_i32_e32 vcc, v140, v139
	s_lshl_b64 s[0:1], s[64:65], 11
	s_add_u32 s66, s90, s0
	v_cndmask_b32_e32 v140, v138, v140, vcc
	v_lshlrev_b32_e32 v208, 2, v140
	v_xor_b32_e32 v140, 8, v138
	v_cmp_lt_i32_e32 vcc, v140, v139
	s_addc_u32 s67, s91, s1
	s_mul_i32 s1, s64, 0x1080
	v_cndmask_b32_e32 v140, v138, v140, vcc
	v_lshlrev_b32_e32 v209, 2, v140
	v_xor_b32_e32 v140, 16, v138
	v_cmp_lt_i32_e32 vcc, v140, v139
	s_mul_hi_i32 s0, s64, 0x1080
	s_add_u32 s68, s90, s1
	v_cndmask_b32_e32 v140, v138, v140, vcc
	v_lshlrev_b32_e32 v210, 2, v140
	v_xor_b32_e32 v140, 32, v138
	v_cmp_lt_i32_e32 vcc, v140, v139
	s_mov_b32 s3, 0
	v_lshlrev_b64 v[136:137], 1, v[136:137]
	v_cndmask_b32_e32 v138, v138, v140, vcc
	v_lshlrev_b32_e32 v211, 2, v138
	s_addc_u32 s69, s91, s0
	s_mov_b32 s33, 0x12500000
	s_mov_b32 s56, 0x12501000
	s_mov_b32 s57, 0x12502000
	s_mov_b32 s58, 0x12503000
	v_mov_b32_e32 v212, 0x358637bd
	s_mov_b32 s59, 0xf800000
	v_mov_b32_e32 v213, 0x260
	s_mov_b32 s60, 0xa400000
	s_mov_b32 s61, 0xa401000
	v_readlane_b32 s16, v255, 8
	v_readlane_b32 s17, v255, 9
	v_readlane_b32 s18, v255, 10
	v_readlane_b32 s19, v255, 11
	v_readlane_b32 s20, v255, 12
	v_readlane_b32 s21, v255, 13
	v_readlane_b32 s22, v255, 14
	v_readlane_b32 s23, v255, 15
	v_readlane_b32 s24, v255, 16
	v_readlane_b32 s25, v255, 17
	v_readlane_b32 s26, v255, 18
	v_readlane_b32 s27, v255, 19
; DI void conv_unit(int item, const bf16_t* __restrict__ P, bf16_t* __restrict__ Y, const float* __restrict__ cw, const float* __restrict__ cb,
;                   const float* __restrict__ lng, const float* __restrict__ lnb, int lane) {
;     ...
;     for (int ps = 0; ps < 4; ++ps) {
;         const int tok = tok0 + 4 * ps, tl = tok & (SEQ - 1);
;         const bf16_t* src = P + (size_t)tok * PW + P_CV + 4 * lane;
;         u32x2 r[34];
; #pragma unroll
;         for (int i = 0; i < 34; ++i) { const bool ok = (tl - 30 + i) >= 0; const u32x2 v = *(const u32x2*)(src + (ok ? (i - 30) * PW : 0)); r[i].x = ok ? v.x : 0u; r[i].y = ok ? v.y : 0u; }
.LBB0_703:
	s_add_i32 s0, s64, s3
	s_and_b32 s62, s0, 0x1ffc
	v_lshl_add_u64 v[140:141], s[66:67], 0, v[136:137]
	s_cmp_gt_u32 s62, 29
	v_add_co_u32_e32 v142, vcc, s60, v140
	s_cselect_b64 s[54:55], -1, 0
	s_nop 0
	v_addc_co_u32_e32 v143, vcc, 0, v141, vcc
	s_and_b64 s[0:1], s[54:55], exec
	v_lshl_add_u64 v[138:139], s[68:69], 0, v[136:137]
	v_add_co_u32_e32 v140, vcc, s61, v140
	s_cselect_b32 s1, -1, 0
	s_cselect_b32 s0, 0xfffe1100, 0
	s_cmp_gt_u32 s62, 28
	v_addc_co_u32_e32 v141, vcc, 0, v141, vcc
	v_lshl_add_u64 v[144:145], v[138:139], 0, s[0:1]
	s_cselect_b64 s[52:53], -1, 0
	v_add_co_u32_e32 v144, vcc, 0x12500000, v144
	s_and_b64 s[0:1], s[52:53], exec
	s_nop 0
	v_addc_co_u32_e32 v145, vcc, 0, v145, vcc
	s_cselect_b32 s1, -1, 0
	s_cselect_b32 s0, 0xfffe2180, 0
	s_cmp_gt_u32 s62, 27
	global_load_dwordx2 v[194:195], v[144:145], off
	v_lshl_add_u64 v[144:145], v[138:139], 0, s[0:1]
	s_cselect_b64 s[50:51], -1, 0
	v_add_co_u32_e32 v144, vcc, s33, v144
	s_and_b64 s[0:1], s[50:51], exec
	s_nop 0
	v_addc_co_u32_e32 v145, vcc, 0, v145, vcc
	s_cselect_b32 s1, -1, 0
	s_cselect_b32 s0, 0xfffe3200, 0
	s_cmp_gt_u32 s62, 26
	global_load_dwordx2 v[192:193], v[144:145], off
	v_lshl_add_u64 v[144:145], v[138:139], 0, s[0:1]
	s_cselect_b64 s[48:49], -1, 0
	v_add_co_u32_e32 v144, vcc, s33, v144
	s_and_b64 s[0:1], s[48:49], exec
	s_nop 0
	v_addc_co_u32_e32 v145, vcc, 0, v145, vcc
	s_cselect_b32 s1, -1, 0
	s_cselect_b32 s0, 0xfffe4280, 0
	s_cmp_gt_u32 s62, 25
	global_load_dwordx2 v[190:191], v[144:145], off
	v_lshl_add_u64 v[144:145], v[138:139], 0, s[0:1]
	s_cselect_b64 s[46:47], -1, 0
	v_add_co_u32_e32 v144, vcc, s33, v144
	s_and_b64 s[0:1], s[46:47], exec
	s_nop 0
	v_addc_co_u32_e32 v145, vcc, 0, v145, vcc
	s_cselect_b32 s1, -1, 0
	s_cselect_b32 s0, 0xfffe5300, 0
	s_cmp_gt_u32 s62, 24
	global_load_dwordx2 v[188:189], v[144:145], off
	v_lshl_add_u64 v[144:145], v[138:139], 0, s[0:1]
	s_cselect_b64 s[44:45], -1, 0
	v_add_co_u32_e32 v144, vcc, s33, v144
	s_and_b64 s[0:1], s[44:45], exec
	s_nop 0
	v_addc_co_u32_e32 v145, vcc, 0, v145, vcc
	s_cselect_b32 s1, -1, 0
	s_cselect_b32 s0, 0xfffe6380, 0
	s_cmp_gt_u32 s62, 23
	global_load_dwordx2 v[186:187], v[144:145], off
	v_lshl_add_u64 v[144:145], v[138:139], 0, s[0:1]
	s_cselect_b64 s[42:43], -1, 0
	v_add_co_u32_e32 v144, vcc, s33, v144
	s_and_b64 s[0:1], s[42:43], exec
	s_nop 0
	v_addc_co_u32_e32 v145, vcc, 0, v145, vcc
	s_cselect_b32 s1, -1, 0
	s_cselect_b32 s0, 0xfffe7400, 0
	s_cmp_gt_u32 s62, 22
	global_load_dwordx2 v[184:185], v[144:145], off
	v_lshl_add_u64 v[144:145], v[138:139], 0, s[0:1]
	s_cselect_b64 s[40:41], -1, 0
	v_add_co_u32_e32 v144, vcc, s33, v144
	s_and_b64 s[0:1], s[40:41], exec
	s_nop 0
	v_addc_co_u32_e32 v145, vcc, 0, v145, vcc
	s_cselect_b32 s1, -1, 0
	s_cselect_b32 s0, 0xfffe8480, 0
	s_cmp_gt_u32 s62, 21
	global_load_dwordx2 v[182:183], v[144:145], off
	v_lshl_add_u64 v[144:145], v[138:139], 0, s[0:1]
	s_cselect_b64 s[38:39], -1, 0
	v_add_co_u32_e32 v144, vcc, s33, v144
	s_and_b64 s[0:1], s[38:39], exec
	s_nop 0
	v_addc_co_u32_e32 v145, vcc, 0, v145, vcc
	s_cselect_b32 s1, -1, 0
	s_cselect_b32 s0, 0xfffe9500, 0
	s_cmp_gt_u32 s62, 20
	global_load_dwordx2 v[180:181], v[144:145], off
	v_lshl_add_u64 v[144:145], v[138:139], 0, s[0:1]
	s_cselect_b64 s[36:37], -1, 0
	v_add_co_u32_e32 v144, vcc, s33, v144
	s_and_b64 s[0:1], s[36:37], exec
	s_nop 0
	v_addc_co_u32_e32 v145, vcc, 0, v145, vcc
	s_cselect_b32 s1, -1, 0
	s_cselect_b32 s0, 0xfffea580, 0
	s_cmp_gt_u32 s62, 19
	global_load_dwordx2 v[178:179], v[144:145], off
	v_lshl_add_u64 v[144:145], v[138:139], 0, s[0:1]
	s_cselect_b64 s[34:35], -1, 0
	v_add_co_u32_e32 v144, vcc, s33, v144
	s_and_b64 s[0:1], s[34:35], exec
	s_nop 0
	v_addc_co_u32_e32 v145, vcc, 0, v145, vcc
	s_cselect_b32 s1, -1, 0
	s_cselect_b32 s0, 0xfffeb600, 0
	s_cmp_gt_u32 s62, 18
	global_load_dwordx2 v[176:177], v[144:145], off
	v_lshl_add_u64 v[144:145], v[138:139], 0, s[0:1]
	s_cselect_b64 s[30:31], -1, 0
	v_add_co_u32_e32 v144, vcc, s33, v144
	s_and_b64 s[0:1], s[30:31], exec
	s_nop 0
	v_addc_co_u32_e32 v145, vcc, 0, v145, vcc
	s_cselect_b32 s1, -1, 0
	s_cselect_b32 s0, 0xfffec680, 0
	s_cmp_gt_u32 s62, 17
	global_load_dwordx2 v[174:175], v[144:145], off
	v_lshl_add_u64 v[144:145], v[138:139], 0, s[0:1]
	s_cselect_b64 s[28:29], -1, 0
	v_add_co_u32_e32 v144, vcc, s33, v144
	s_and_b64 s[0:1], s[28:29], exec
	s_nop 0
	v_addc_co_u32_e32 v145, vcc, 0, v145, vcc
	s_cselect_b32 s1, -1, 0
	s_cselect_b32 s0, 0xfffed700, 0
	s_cmp_gt_u32 s62, 16
	global_load_dwordx2 v[172:173], v[144:145], off
	v_lshl_add_u64 v[144:145], v[138:139], 0, s[0:1]
	s_cselect_b64 s[26:27], -1, 0
	v_add_co_u32_e32 v144, vcc, s33, v144
	s_and_b64 s[0:1], s[26:27], exec
	s_nop 0
	v_addc_co_u32_e32 v145, vcc, 0, v145, vcc
	s_cselect_b32 s1, -1, 0
	s_cselect_b32 s0, 0xfffee780, 0
	s_cmp_gt_u32 s62, 15
	global_load_dwordx2 v[170:171], v[144:145], off
	v_lshl_add_u64 v[144:145], v[138:139], 0, s[0:1]
	s_cselect_b64 s[24:25], -1, 0
	v_add_co_u32_e32 v144, vcc, s33, v144
	s_and_b64 s[0:1], s[24:25], exec
	s_nop 0
	v_addc_co_u32_e32 v145, vcc, 0, v145, vcc
	s_cselect_b32 s1, -1, 0
	s_cselect_b32 s0, 0xfffef800, 0
	s_cmp_gt_u32 s62, 14
	global_load_dwordx2 v[168:169], v[144:145], off
	v_lshl_add_u64 v[144:145], v[138:139], 0, s[0:1]
	s_cselect_b64 s[22:23], -1, 0
	v_add_co_u32_e32 v144, vcc, s33, v144
	s_and_b64 s[0:1], s[22:23], exec
	s_nop 0
	v_addc_co_u32_e32 v145, vcc, 0, v145, vcc
	s_cselect_b32 s1, -1, 0
	s_cselect_b32 s0, 0xffff0880, 0
	s_cmp_gt_u32 s62, 13
	global_load_dwordx2 v[166:167], v[144:145], off
	v_lshl_add_u64 v[144:145], v[138:139], 0, s[0:1]
	s_cselect_b64 s[20:21], -1, 0
	v_add_co_u32_e32 v144, vcc, s33, v144
; DI void conv_unit(int item, const bf16_t* __restrict__ P, bf16_t* __restrict__ Y, const float* __restrict__ cw, const float* __restrict__ cb,
;                   const float* __restrict__ lng, const float* __restrict__ lnb, int lane) {
;     ...
;         for (int i = 0; i < 34; ++i) { const bool ok = (tl - 30 + i) >= 0; const u32x2 v = *(const u32x2*)(src + (ok ? (i - 30) * PW : 0)); r[i].x = ok ? v.x : 0u; r[i].y = ok ? v.y : 0u; }
	s_and_b64 s[0:1], s[20:21], exec
	s_nop 0
	v_addc_co_u32_e32 v145, vcc, 0, v145, vcc
	s_cselect_b32 s1, -1, 0
	s_cselect_b32 s0, 0xffff1900, 0
	s_cmp_gt_u32 s62, 12
	global_load_dwordx2 v[164:165], v[144:145], off
	v_lshl_add_u64 v[144:145], v[138:139], 0, s[0:1]
	s_cselect_b64 s[18:19], -1, 0
	v_add_co_u32_e32 v144, vcc, s33, v144
	s_and_b64 s[0:1], s[18:19], exec
	s_nop 0
	v_addc_co_u32_e32 v145, vcc, 0, v145, vcc
	s_cselect_b32 s1, -1, 0
	s_cselect_b32 s0, 0xffff2980, 0
	s_cmp_gt_u32 s62, 11
	global_load_dwordx2 v[162:163], v[144:145], off
	v_lshl_add_u64 v[144:145], v[138:139], 0, s[0:1]
	s_cselect_b64 s[16:17], -1, 0
	v_add_co_u32_e32 v144, vcc, s33, v144
	s_and_b64 s[0:1], s[16:17], exec
	s_nop 0
	v_addc_co_u32_e32 v145, vcc, 0, v145, vcc
	s_cselect_b32 s1, -1, 0
	s_cselect_b32 s0, 0xffff3a00, 0
	s_cmp_gt_u32 s62, 10
	global_load_dwordx2 v[160:161], v[144:145], off
	v_lshl_add_u64 v[144:145], v[138:139], 0, s[0:1]
	s_cselect_b64 s[14:15], -1, 0
	v_add_co_u32_e32 v144, vcc, s33, v144
	s_and_b64 s[0:1], s[14:15], exec
	s_nop 0
	v_addc_co_u32_e32 v145, vcc, 0, v145, vcc
	s_cselect_b32 s1, -1, 0
	s_cselect_b32 s0, 0xffff4a80, 0
	s_cmp_gt_u32 s62, 9
	global_load_dwordx2 v[158:159], v[144:145], off
	v_lshl_add_u64 v[144:145], v[138:139], 0, s[0:1]
	s_cselect_b64 s[12:13], -1, 0
	v_add_co_u32_e32 v144, vcc, s33, v144
	s_and_b64 s[0:1], s[12:13], exec
	s_nop 0
	v_addc_co_u32_e32 v145, vcc, 0, v145, vcc
	s_cselect_b32 s1, -1, 0
	s_cselect_b32 s0, 0xffff5b00, 0
	s_cmp_gt_u32 s62, 8
	global_load_dwordx2 v[156:157], v[144:145], off
	v_lshl_add_u64 v[144:145], v[138:139], 0, s[0:1]
	s_cselect_b64 s[10:11], -1, 0
	v_add_co_u32_e32 v144, vcc, s33, v144
	s_and_b64 s[0:1], s[10:11], exec
	s_nop 0
	v_addc_co_u32_e32 v145, vcc, 0, v145, vcc
	s_cselect_b32 s1, -1, 0
	s_cselect_b32 s0, 0xffff6b80, 0
	s_cmp_gt_u32 s62, 7
	global_load_dwordx2 v[154:155], v[144:145], off
	v_lshl_add_u64 v[144:145], v[138:139], 0, s[0:1]
	s_cselect_b64 s[8:9], -1, 0
	v_add_co_u32_e32 v144, vcc, s33, v144
	s_and_b64 s[0:1], s[8:9], exec
	s_nop 0
	v_addc_co_u32_e32 v145, vcc, 0, v145, vcc
	s_cselect_b32 s1, -1, 0
	s_cselect_b32 s0, 0xffff7c00, 0
	s_cmp_gt_u32 s62, 6
	global_load_dwordx2 v[152:153], v[144:145], off
	v_lshl_add_u64 v[144:145], v[138:139], 0, s[0:1]
	s_cselect_b64 s[6:7], -1, 0
	v_add_co_u32_e32 v144, vcc, s33, v144
	s_and_b64 s[0:1], s[6:7], exec
	s_nop 0
	v_addc_co_u32_e32 v145, vcc, 0, v145, vcc
	s_cselect_b32 s1, -1, 0
	s_cselect_b32 s0, 0xffff8c80, 0
	s_cmp_gt_u32 s62, 5
	global_load_dwordx2 v[150:151], v[144:145], off
	v_lshl_add_u64 v[144:145], v[138:139], 0, s[0:1]
	s_cselect_b64 s[4:5], -1, 0
	v_add_co_u32_e32 v144, vcc, s33, v144
	s_and_b64 s[0:1], s[4:5], exec
	s_nop 0
	v_addc_co_u32_e32 v145, vcc, 0, v145, vcc
	s_cselect_b32 s1, -1, 0
	s_cselect_b32 s0, 0xffff9d00, 0
	s_cmp_gt_u32 s62, 4
	global_load_dwordx2 v[148:149], v[144:145], off
	v_lshl_add_u64 v[144:145], v[138:139], 0, s[0:1]
	s_cselect_b64 s[0:1], -1, 0
	s_and_b64 s[70:71], s[0:1], exec
	v_add_co_u32_e32 v144, vcc, s33, v144
	s_cselect_b32 s71, -1, 0
	s_cselect_b32 s70, 0xffffad80, 0
	s_cmp_eq_u32 s62, 0
	v_addc_co_u32_e32 v145, vcc, 0, v145, vcc
	s_cselect_b64 s[72:73], -1, 0
	global_load_dwordx2 v[146:147], v[144:145], off
	v_lshl_add_u64 v[144:145], v[138:139], 0, s[70:71]
	s_and_b64 s[62:63], s[72:73], exec
	v_add_co_u32_e32 v144, vcc, s33, v144
	s_cselect_b32 s75, 0, -1
	s_cselect_b32 s74, 0, 0xffffbe00
	v_addc_co_u32_e32 v145, vcc, 0, v145, vcc
	v_lshl_add_u64 v[196:197], v[138:139], 0, s[74:75]
	s_cselect_b32 s74, 0, 0xffffce80
	v_add_co_u32_e32 v196, vcc, s33, v196
	v_lshl_add_u64 v[198:199], v[138:139], 0, s[74:75]
	s_nop 0
	v_addc_co_u32_e32 v197, vcc, 0, v197, vcc
	s_cselect_b32 s74, 0, 0xffffef80
	v_add_co_u32_e32 v198, vcc, s33, v198
	v_lshl_add_u64 v[202:203], s[74:75], 1, v[138:139]
	s_nop 0
	v_addc_co_u32_e32 v199, vcc, 0, v199, vcc
	v_add_co_u32_e32 v202, vcc, s33, v202
	v_lshl_add_u64 v[204:205], v[138:139], 0, s[74:75]
	s_nop 0
	v_addc_co_u32_e32 v203, vcc, 0, v203, vcc
	global_load_dwordx2 v[144:145], v[144:145], off
	s_nop 0
	global_load_dwordx2 v[200:201], v[196:197], off
	s_nop 0
	global_load_dwordx2 v[198:199], v[198:199], off
	v_add_co_u32_e32 v196, vcc, s33, v204
	s_waitcnt vmcnt(0)
; DI float bf_lo(unsigned u) { return __uint_as_float(u << 16); }
; DI float bf_hi(unsigned u) { return __uint_as_float(u & 0xffff0000u); }
; DI void conv_unit(int item, const bf16_t* __restrict__ P, bf16_t* __restrict__ Y, const float* __restrict__ cw, const float* __restrict__ cb,
;                   const float* __restrict__ lng, const float* __restrict__ lnb, int lane) {
;     ...
;         for (int tt = 0; tt < 4; ++tt) { acc[tt] = bias;
; #pragma unroll
;             for (int j = 0; j < 31; ++j) { const u32x2 v = r[tt + j]; f32x4 x; x[0] = bf_lo(v.x); x[1] = bf_hi(v.x); x[2] = bf_lo(v.y); x[3] = bf_hi(v.y); acc[tt] += w[j] * x; } }
	v_cndmask_b32_e64 v204, 0, v194, s[54:55]
	v_addc_co_u32_e32 v197, vcc, 0, v205, vcc
	v_add_co_u32_e32 v194, vcc, s33, v138
	v_cndmask_b32_e64 v215, 0, v195, s[54:55]
	s_nop 0
	v_addc_co_u32_e32 v195, vcc, 0, v139, vcc
	global_load_dwordx2 v[202:203], v[202:203], off
	v_add_co_u32_e32 v214, vcc, s56, v138
	v_lshlrev_b32_e32 v218, 16, v215
	v_and_b32_e32 v219, 0xffff0000, v215
	v_addc_co_u32_e32 v215, vcc, 0, v139, vcc
	v_lshlrev_b32_e32 v216, 16, v204
	v_and_b32_e32 v217, 0xffff0000, v204
	global_load_dwordx2 v[204:205], v[196:197], off
	s_nop 0
	global_load_dwordx2 v[196:197], v[194:195], off
	v_add_co_u32_e32 v220, vcc, s57, v138
	global_load_dwordx2 v[194:195], v[214:215], off offset:128
	s_nop 0
	v_addc_co_u32_e32 v221, vcc, 0, v139, vcc
	v_add_co_u32_e32 v138, vcc, s58, v138
	v_cndmask_b32_e64 v192, 0, v192, s[52:53]
	v_cndmask_b32_e64 v193, 0, v193, s[52:53]
	v_addc_co_u32_e32 v139, vcc, 0, v139, vcc
	v_lshlrev_b32_e32 v214, 16, v192
	v_and_b32_e32 v215, 0xffff0000, v192
	v_lshlrev_b32_e32 v222, 16, v193
	v_and_b32_e32 v223, 0xffff0000, v193
	global_load_dwordx2 v[192:193], v[220:221], off offset:256
	s_nop 0
	global_load_dwordx2 v[138:139], v[138:139], off offset:384
	v_pk_fma_f32 v[218:219], v[2:3], v[218:219], v[126:127]
	v_pk_fma_f32 v[216:217], v[0:1], v[216:217], v[124:125]
	v_pk_fma_f32 v[218:219], v[6:7], v[222:223], v[218:219]
	v_pk_fma_f32 v[220:221], v[2:3], v[222:223], v[126:127]
	v_cndmask_b32_e64 v222, 0, v190, s[50:51]
	v_cndmask_b32_e64 v223, 0, v191, s[50:51]
	v_pk_fma_f32 v[216:217], v[4:5], v[214:215], v[216:217]
	v_pk_fma_f32 v[214:215], v[0:1], v[214:215], v[124:125]
	v_lshlrev_b32_e32 v190, 16, v222
	v_and_b32_e32 v191, 0xffff0000, v222
	v_lshlrev_b32_e32 v222, 16, v223
	v_and_b32_e32 v223, 0xffff0000, v223
	v_cndmask_b32_e64 v224, 0, v188, s[48:49]
	v_cndmask_b32_e64 v225, 0, v189, s[48:49]
	v_pk_fma_f32 v[218:219], v[10:11], v[222:223], v[218:219]
	v_pk_fma_f32 v[216:217], v[8:9], v[190:191], v[216:217]
	v_pk_fma_f32 v[214:215], v[4:5], v[190:191], v[214:215]
	v_pk_fma_f32 v[220:221], v[6:7], v[222:223], v[220:221]
	v_pk_fma_f32 v[222:223], v[2:3], v[222:223], v[126:127]
	v_pk_fma_f32 v[190:191], v[0:1], v[190:191], v[124:125]
	v_lshlrev_b32_e32 v188, 16, v224
	v_and_b32_e32 v189, 0xffff0000, v224
	v_lshlrev_b32_e32 v224, 16, v225
	v_and_b32_e32 v225, 0xffff0000, v225
	v_cndmask_b32_e64 v226, 0, v186, s[46:47]
	v_cndmask_b32_e64 v227, 0, v187, s[46:47]
	v_pk_fma_f32 v[216:217], v[12:13], v[188:189], v[216:217]
	v_pk_fma_f32 v[218:219], v[14:15], v[224:225], v[218:219]
	v_pk_fma_f32 v[220:221], v[10:11], v[224:225], v[220:221]
	v_pk_fma_f32 v[214:215], v[8:9], v[188:189], v[214:215]
	v_pk_fma_f32 v[190:191], v[4:5], v[188:189], v[190:191]
	v_pk_fma_f32 v[222:223], v[6:7], v[224:225], v[222:223]
	v_pk_fma_f32 v[224:225], v[2:3], v[224:225], v[126:127]
	v_pk_fma_f32 v[188:189], v[0:1], v[188:189], v[124:125]
	v_lshlrev_b32_e32 v186, 16, v226
	v_and_b32_e32 v187, 0xffff0000, v226
	v_lshlrev_b32_e32 v226, 16, v227
	v_and_b32_e32 v227, 0xffff0000, v227
	v_pk_fma_f32 v[216:217], v[16:17], v[186:187], v[216:217]
	v_pk_fma_f32 v[214:215], v[12:13], v[186:187], v[214:215]
	v_pk_fma_f32 v[190:191], v[8:9], v[186:187], v[190:191]
	v_pk_fma_f32 v[186:187], v[4:5], v[186:187], v[188:189]
	v_pk_fma_f32 v[188:189], v[6:7], v[226:227], v[224:225]
	v_cndmask_b32_e64 v224, 0, v184, s[44:45]
	v_cndmask_b32_e64 v225, 0, v185, s[44:45]
	v_lshlrev_b32_e32 v184, 16, v224
	v_and_b32_e32 v185, 0xffff0000, v224
	v_pk_fma_f32 v[218:219], v[18:19], v[226:227], v[218:219]
	v_pk_fma_f32 v[220:221], v[14:15], v[226:227], v[220:221]
	v_pk_fma_f32 v[222:223], v[10:11], v[226:227], v[222:223]
	v_lshlrev_b32_e32 v224, 16, v225
	v_and_b32_e32 v225, 0xffff0000, v225
	v_pk_fma_f32 v[216:217], v[20:21], v[184:185], v[216:217]
	v_pk_fma_f32 v[214:215], v[16:17], v[184:185], v[214:215]
	v_pk_fma_f32 v[190:191], v[12:13], v[184:185], v[190:191]
	v_pk_fma_f32 v[184:185], v[8:9], v[184:185], v[186:187]
	v_cndmask_b32_e64 v186, 0, v182, s[42:43]
	v_cndmask_b32_e64 v187, 0, v183, s[42:43]
	v_pk_fma_f32 v[218:219], v[22:23], v[224:225], v[218:219]
	v_pk_fma_f32 v[220:221], v[18:19], v[224:225], v[220:221]
	v_pk_fma_f32 v[222:223], v[14:15], v[224:225], v[222:223]
	v_pk_fma_f32 v[188:189], v[10:11], v[224:225], v[188:189]
	v_lshlrev_b32_e32 v182, 16, v186
	v_and_b32_e32 v183, 0xffff0000, v186
	v_lshlrev_b32_e32 v186, 16, v187
	v_and_b32_e32 v187, 0xffff0000, v187
	v_pk_fma_f32 v[218:219], v[26:27], v[186:187], v[218:219]
	v_pk_fma_f32 v[216:217], v[24:25], v[182:183], v[216:217]
	v_pk_fma_f32 v[214:215], v[20:21], v[182:183], v[214:215]
	v_pk_fma_f32 v[220:221], v[22:23], v[186:187], v[220:221]
	v_pk_fma_f32 v[222:223], v[18:19], v[186:187], v[222:223]
	v_pk_fma_f32 v[190:191], v[16:17], v[182:183], v[190:191]
	v_pk_fma_f32 v[182:183], v[12:13], v[182:183], v[184:185]
	v_pk_fma_f32 v[184:185], v[14:15], v[186:187], v[188:189]
	v_cndmask_b32_e64 v186, 0, v180, s[40:41]
	v_cndmask_b32_e64 v187, 0, v181, s[40:41]
	v_lshlrev_b32_e32 v180, 16, v186
	v_and_b32_e32 v181, 0xffff0000, v186
	v_lshlrev_b32_e32 v186, 16, v187
	v_and_b32_e32 v187, 0xffff0000, v187
	v_pk_fma_f32 v[188:189], v[28:29], v[180:181], v[216:217]
	v_pk_fma_f32 v[214:215], v[24:25], v[180:181], v[214:215]
	v_pk_fma_f32 v[190:191], v[20:21], v[180:181], v[190:191]
	v_pk_fma_f32 v[180:181], v[16:17], v[180:181], v[182:183]
	v_cndmask_b32_e64 v182, 0, v178, s[38:39]
	v_cndmask_b32_e64 v183, 0, v179, s[38:39]
	v_pk_fma_f32 v[216:217], v[30:31], v[186:187], v[218:219]
	v_pk_fma_f32 v[218:219], v[26:27], v[186:187], v[220:221]
	v_pk_fma_f32 v[220:221], v[22:23], v[186:187], v[222:223]
; DI float bf_lo(unsigned u) { return __uint_as_float(u << 16); }
; DI float bf_hi(unsigned u) { return __uint_as_float(u & 0xffff0000u); }
; DI void conv_unit(int item, const bf16_t* __restrict__ P, bf16_t* __restrict__ Y, const float* __restrict__ cw, const float* __restrict__ cb,
;                   const float* __restrict__ lng, const float* __restrict__ lnb, int lane) {
;     ...
;         for (int tt = 0; tt < 4; ++tt) { acc[tt] = bias;
; #pragma unroll
;             for (int j = 0; j < 31; ++j) { const u32x2 v = r[tt + j]; f32x4 x; x[0] = bf_lo(v.x); x[1] = bf_hi(v.x); x[2] = bf_lo(v.y); x[3] = bf_hi(v.y); acc[tt] += w[j] * x; } }
	v_pk_fma_f32 v[184:185], v[18:19], v[186:187], v[184:185]
	v_lshlrev_b32_e32 v178, 16, v182
	v_and_b32_e32 v179, 0xffff0000, v182
	v_lshlrev_b32_e32 v182, 16, v183
	v_and_b32_e32 v183, 0xffff0000, v183
	v_pk_fma_f32 v[186:187], v[34:35], v[182:183], v[216:217]
	v_pk_fma_f32 v[188:189], v[32:33], v[178:179], v[188:189]
	v_pk_fma_f32 v[214:215], v[28:29], v[178:179], v[214:215]
	v_pk_fma_f32 v[216:217], v[30:31], v[182:183], v[218:219]
	v_pk_fma_f32 v[218:219], v[26:27], v[182:183], v[220:221]
	v_pk_fma_f32 v[190:191], v[24:25], v[178:179], v[190:191]
	v_pk_fma_f32 v[178:179], v[20:21], v[178:179], v[180:181]
	v_pk_fma_f32 v[180:181], v[22:23], v[182:183], v[184:185]
	v_cndmask_b32_e64 v182, 0, v176, s[36:37]
	v_cndmask_b32_e64 v183, 0, v177, s[36:37]
	v_lshlrev_b32_e32 v176, 16, v182
	v_and_b32_e32 v177, 0xffff0000, v182
	v_lshlrev_b32_e32 v182, 16, v183
	v_and_b32_e32 v183, 0xffff0000, v183
	v_pk_fma_f32 v[184:185], v[36:37], v[176:177], v[188:189]
	v_pk_fma_f32 v[214:215], v[32:33], v[176:177], v[214:215]
	v_pk_fma_f32 v[190:191], v[28:29], v[176:177], v[190:191]
	v_pk_fma_f32 v[176:177], v[24:25], v[176:177], v[178:179]
	v_cndmask_b32_e64 v178, 0, v174, s[34:35]
	v_cndmask_b32_e64 v179, 0, v175, s[34:35]
	v_pk_fma_f32 v[186:187], v[38:39], v[182:183], v[186:187]
	v_pk_fma_f32 v[188:189], v[34:35], v[182:183], v[216:217]
	v_pk_fma_f32 v[216:217], v[30:31], v[182:183], v[218:219]
	v_pk_fma_f32 v[180:181], v[26:27], v[182:183], v[180:181]
	v_lshlrev_b32_e32 v174, 16, v178
	v_and_b32_e32 v175, 0xffff0000, v178
	v_lshlrev_b32_e32 v178, 16, v179
	v_and_b32_e32 v179, 0xffff0000, v179
	v_pk_fma_f32 v[182:183], v[42:43], v[178:179], v[186:187]
	v_pk_fma_f32 v[184:185], v[40:41], v[174:175], v[184:185]
	v_pk_fma_f32 v[186:187], v[36:37], v[174:175], v[214:215]
	v_pk_fma_f32 v[188:189], v[38:39], v[178:179], v[188:189]
	v_pk_fma_f32 v[214:215], v[34:35], v[178:179], v[216:217]
	v_pk_fma_f32 v[190:191], v[32:33], v[174:175], v[190:191]
	v_pk_fma_f32 v[174:175], v[28:29], v[174:175], v[176:177]
	v_pk_fma_f32 v[176:177], v[30:31], v[178:179], v[180:181]
	v_cndmask_b32_e64 v178, 0, v172, s[30:31]
	v_cndmask_b32_e64 v179, 0, v173, s[30:31]
	v_lshlrev_b32_e32 v172, 16, v178
	v_and_b32_e32 v173, 0xffff0000, v178
	v_lshlrev_b32_e32 v178, 16, v179
	v_and_b32_e32 v179, 0xffff0000, v179
	v_pk_fma_f32 v[180:181], v[44:45], v[172:173], v[184:185]
	v_pk_fma_f32 v[184:185], v[42:43], v[178:179], v[188:189]
	v_pk_fma_f32 v[186:187], v[40:41], v[172:173], v[186:187]
	v_pk_fma_f32 v[188:189], v[36:37], v[172:173], v[190:191]
	v_pk_fma_f32 v[172:173], v[32:33], v[172:173], v[174:175]
	v_cndmask_b32_e64 v174, 0, v170, s[28:29]
	v_cndmask_b32_e64 v175, 0, v171, s[28:29]
	v_pk_fma_f32 v[182:183], v[46:47], v[178:179], v[182:183]
	v_pk_fma_f32 v[190:191], v[38:39], v[178:179], v[214:215]
	v_pk_fma_f32 v[176:177], v[34:35], v[178:179], v[176:177]
	v_lshlrev_b32_e32 v170, 16, v174
	v_and_b32_e32 v171, 0xffff0000, v174
	v_lshlrev_b32_e32 v174, 16, v175
	v_and_b32_e32 v175, 0xffff0000, v175
	v_pk_fma_f32 v[178:179], v[50:51], v[174:175], v[182:183]
	v_pk_fma_f32 v[180:181], v[48:49], v[170:171], v[180:181]
	v_pk_fma_f32 v[182:183], v[44:45], v[170:171], v[186:187]
	v_pk_fma_f32 v[184:185], v[46:47], v[174:175], v[184:185]
	v_pk_fma_f32 v[186:187], v[42:43], v[174:175], v[190:191]
	v_pk_fma_f32 v[188:189], v[40:41], v[170:171], v[188:189]
	v_pk_fma_f32 v[170:171], v[36:37], v[170:171], v[172:173]
	v_pk_fma_f32 v[172:173], v[38:39], v[174:175], v[176:177]
	v_cndmask_b32_e64 v174, 0, v168, s[26:27]
	v_cndmask_b32_e64 v175, 0, v169, s[26:27]
	v_lshlrev_b32_e32 v168, 16, v174
	v_and_b32_e32 v169, 0xffff0000, v174
	v_lshlrev_b32_e32 v174, 16, v175
	v_and_b32_e32 v175, 0xffff0000, v175
	v_pk_fma_f32 v[176:177], v[52:53], v[168:169], v[180:181]
	v_pk_fma_f32 v[180:181], v[50:51], v[174:175], v[184:185]
	v_pk_fma_f32 v[182:183], v[48:49], v[168:169], v[182:183]
	v_pk_fma_f32 v[184:185], v[44:45], v[168:169], v[188:189]
	v_pk_fma_f32 v[168:169], v[40:41], v[168:169], v[170:171]
	v_cndmask_b32_e64 v170, 0, v166, s[24:25]
	v_cndmask_b32_e64 v171, 0, v167, s[24:25]
	v_pk_fma_f32 v[178:179], v[54:55], v[174:175], v[178:179]
	v_pk_fma_f32 v[186:187], v[46:47], v[174:175], v[186:187]
	v_pk_fma_f32 v[172:173], v[42:43], v[174:175], v[172:173]
	v_lshlrev_b32_e32 v166, 16, v170
	v_and_b32_e32 v167, 0xffff0000, v170
	v_lshlrev_b32_e32 v170, 16, v171
	v_and_b32_e32 v171, 0xffff0000, v171
	v_pk_fma_f32 v[174:175], v[58:59], v[170:171], v[178:179]
	v_pk_fma_f32 v[176:177], v[56:57], v[166:167], v[176:177]
	v_pk_fma_f32 v[178:179], v[52:53], v[166:167], v[182:183]
	v_pk_fma_f32 v[180:181], v[54:55], v[170:171], v[180:181]
	v_pk_fma_f32 v[182:183], v[50:51], v[170:171], v[186:187]
	v_pk_fma_f32 v[184:185], v[48:49], v[166:167], v[184:185]
	v_pk_fma_f32 v[166:167], v[44:45], v[166:167], v[168:169]
	v_pk_fma_f32 v[168:169], v[46:47], v[170:171], v[172:173]
	v_cndmask_b32_e64 v170, 0, v164, s[22:23]
	v_cndmask_b32_e64 v171, 0, v165, s[22:23]
	v_lshlrev_b32_e32 v164, 16, v170
	v_and_b32_e32 v165, 0xffff0000, v170
	v_lshlrev_b32_e32 v170, 16, v171
	v_and_b32_e32 v171, 0xffff0000, v171
	v_pk_fma_f32 v[172:173], v[60:61], v[164:165], v[176:177]
	v_pk_fma_f32 v[176:177], v[58:59], v[170:171], v[180:181]
	v_pk_fma_f32 v[178:179], v[56:57], v[164:165], v[178:179]
	v_pk_fma_f32 v[180:181], v[52:53], v[164:165], v[184:185]
	v_pk_fma_f32 v[164:165], v[48:49], v[164:165], v[166:167]
	v_cndmask_b32_e64 v166, 0, v162, s[20:21]
	v_cndmask_b32_e64 v167, 0, v163, s[20:21]
	v_pk_fma_f32 v[174:175], v[62:63], v[170:171], v[174:175]
	v_pk_fma_f32 v[182:183], v[54:55], v[170:171], v[182:183]
; DI float bf_lo(unsigned u) { return __uint_as_float(u << 16); }
; DI float bf_hi(unsigned u) { return __uint_as_float(u & 0xffff0000u); }
; DI void conv_unit(int item, const bf16_t* __restrict__ P, bf16_t* __restrict__ Y, const float* __restrict__ cw, const float* __restrict__ cb,
;                   const float* __restrict__ lng, const float* __restrict__ lnb, int lane) {
;     ...
;         for (int tt = 0; tt < 4; ++tt) { acc[tt] = bias;
; #pragma unroll
;             for (int j = 0; j < 31; ++j) { const u32x2 v = r[tt + j]; f32x4 x; x[0] = bf_lo(v.x); x[1] = bf_hi(v.x); x[2] = bf_lo(v.y); x[3] = bf_hi(v.y); acc[tt] += w[j] * x; } }
	v_pk_fma_f32 v[168:169], v[50:51], v[170:171], v[168:169]
	v_lshlrev_b32_e32 v162, 16, v166
	v_and_b32_e32 v163, 0xffff0000, v166
	v_lshlrev_b32_e32 v166, 16, v167
	v_and_b32_e32 v167, 0xffff0000, v167
	v_pk_fma_f32 v[170:171], v[66:67], v[166:167], v[174:175]
	v_pk_fma_f32 v[172:173], v[64:65], v[162:163], v[172:173]
	v_pk_fma_f32 v[174:175], v[60:61], v[162:163], v[178:179]
	v_pk_fma_f32 v[176:177], v[62:63], v[166:167], v[176:177]
	v_pk_fma_f32 v[178:179], v[58:59], v[166:167], v[182:183]
	v_pk_fma_f32 v[180:181], v[56:57], v[162:163], v[180:181]
	v_pk_fma_f32 v[162:163], v[52:53], v[162:163], v[164:165]
	v_pk_fma_f32 v[164:165], v[54:55], v[166:167], v[168:169]
	v_cndmask_b32_e64 v166, 0, v160, s[18:19]
	v_cndmask_b32_e64 v167, 0, v161, s[18:19]
	v_lshlrev_b32_e32 v160, 16, v166
	v_and_b32_e32 v161, 0xffff0000, v166
	v_lshlrev_b32_e32 v166, 16, v167
	v_and_b32_e32 v167, 0xffff0000, v167
	v_pk_fma_f32 v[168:169], v[68:69], v[160:161], v[172:173]
	v_pk_fma_f32 v[172:173], v[66:67], v[166:167], v[176:177]
	v_pk_fma_f32 v[174:175], v[64:65], v[160:161], v[174:175]
	v_pk_fma_f32 v[176:177], v[60:61], v[160:161], v[180:181]
	v_pk_fma_f32 v[160:161], v[56:57], v[160:161], v[162:163]
	v_cndmask_b32_e64 v162, 0, v158, s[16:17]
	v_cndmask_b32_e64 v163, 0, v159, s[16:17]
	v_pk_fma_f32 v[170:171], v[70:71], v[166:167], v[170:171]
	v_pk_fma_f32 v[178:179], v[62:63], v[166:167], v[178:179]
	v_pk_fma_f32 v[164:165], v[58:59], v[166:167], v[164:165]
	v_lshlrev_b32_e32 v158, 16, v162
	v_and_b32_e32 v159, 0xffff0000, v162
	v_lshlrev_b32_e32 v162, 16, v163
	v_and_b32_e32 v163, 0xffff0000, v163
	v_pk_fma_f32 v[166:167], v[74:75], v[162:163], v[170:171]
	v_pk_fma_f32 v[168:169], v[72:73], v[158:159], v[168:169]
	v_pk_fma_f32 v[170:171], v[68:69], v[158:159], v[174:175]
	v_pk_fma_f32 v[172:173], v[70:71], v[162:163], v[172:173]
	v_pk_fma_f32 v[174:175], v[66:67], v[162:163], v[178:179]
	v_pk_fma_f32 v[176:177], v[64:65], v[158:159], v[176:177]
	v_pk_fma_f32 v[158:159], v[60:61], v[158:159], v[160:161]
	v_pk_fma_f32 v[160:161], v[62:63], v[162:163], v[164:165]
	v_cndmask_b32_e64 v162, 0, v156, s[14:15]
	v_cndmask_b32_e64 v163, 0, v157, s[14:15]
	v_lshlrev_b32_e32 v156, 16, v162
	v_and_b32_e32 v157, 0xffff0000, v162
	v_lshlrev_b32_e32 v162, 16, v163
	v_and_b32_e32 v163, 0xffff0000, v163
	v_pk_fma_f32 v[164:165], v[76:77], v[156:157], v[168:169]
	v_pk_fma_f32 v[168:169], v[74:75], v[162:163], v[172:173]
	v_pk_fma_f32 v[170:171], v[72:73], v[156:157], v[170:171]
	v_pk_fma_f32 v[172:173], v[68:69], v[156:157], v[176:177]
	v_pk_fma_f32 v[156:157], v[64:65], v[156:157], v[158:159]
	v_cndmask_b32_e64 v158, 0, v154, s[12:13]
	v_cndmask_b32_e64 v159, 0, v155, s[12:13]
	v_pk_fma_f32 v[166:167], v[78:79], v[162:163], v[166:167]
	v_pk_fma_f32 v[174:175], v[70:71], v[162:163], v[174:175]
	v_pk_fma_f32 v[160:161], v[66:67], v[162:163], v[160:161]
	v_lshlrev_b32_e32 v154, 16, v158
	v_and_b32_e32 v155, 0xffff0000, v158
	v_lshlrev_b32_e32 v158, 16, v159
	v_and_b32_e32 v159, 0xffff0000, v159
	v_pk_fma_f32 v[162:163], v[82:83], v[158:159], v[166:167]
	v_pk_fma_f32 v[164:165], v[80:81], v[154:155], v[164:165]
	v_pk_fma_f32 v[166:167], v[76:77], v[154:155], v[170:171]
	v_pk_fma_f32 v[168:169], v[78:79], v[158:159], v[168:169]
	v_pk_fma_f32 v[170:171], v[74:75], v[158:159], v[174:175]
	v_pk_fma_f32 v[172:173], v[72:73], v[154:155], v[172:173]
	v_pk_fma_f32 v[154:155], v[68:69], v[154:155], v[156:157]
	v_pk_fma_f32 v[156:157], v[70:71], v[158:159], v[160:161]
	v_cndmask_b32_e64 v158, 0, v152, s[10:11]
	v_cndmask_b32_e64 v159, 0, v153, s[10:11]
	v_lshlrev_b32_e32 v152, 16, v158
	v_and_b32_e32 v153, 0xffff0000, v158
	v_lshlrev_b32_e32 v158, 16, v159
	v_and_b32_e32 v159, 0xffff0000, v159
	v_pk_fma_f32 v[160:161], v[84:85], v[152:153], v[164:165]
	v_pk_fma_f32 v[164:165], v[82:83], v[158:159], v[168:169]
	v_pk_fma_f32 v[166:167], v[80:81], v[152:153], v[166:167]
	v_pk_fma_f32 v[168:169], v[76:77], v[152:153], v[172:173]
	v_pk_fma_f32 v[152:153], v[72:73], v[152:153], v[154:155]
	v_cndmask_b32_e64 v154, 0, v150, s[8:9]
	v_cndmask_b32_e64 v155, 0, v151, s[8:9]
	v_pk_fma_f32 v[162:163], v[86:87], v[158:159], v[162:163]
	v_pk_fma_f32 v[170:171], v[78:79], v[158:159], v[170:171]
	v_pk_fma_f32 v[156:157], v[74:75], v[158:159], v[156:157]
	v_lshlrev_b32_e32 v150, 16, v154
	v_and_b32_e32 v151, 0xffff0000, v154
	v_lshlrev_b32_e32 v154, 16, v155
	v_and_b32_e32 v155, 0xffff0000, v155
	v_pk_fma_f32 v[158:159], v[90:91], v[154:155], v[162:163]
	v_pk_fma_f32 v[160:161], v[88:89], v[150:151], v[160:161]
	v_pk_fma_f32 v[162:163], v[84:85], v[150:151], v[166:167]
	v_pk_fma_f32 v[164:165], v[86:87], v[154:155], v[164:165]
	v_pk_fma_f32 v[166:167], v[82:83], v[154:155], v[170:171]
	v_pk_fma_f32 v[168:169], v[80:81], v[150:151], v[168:169]
	v_pk_fma_f32 v[150:151], v[76:77], v[150:151], v[152:153]
	v_pk_fma_f32 v[152:153], v[78:79], v[154:155], v[156:157]
	v_cndmask_b32_e64 v154, 0, v148, s[6:7]
	v_cndmask_b32_e64 v155, 0, v149, s[6:7]
	v_lshlrev_b32_e32 v148, 16, v154
	v_and_b32_e32 v149, 0xffff0000, v154
	v_lshlrev_b32_e32 v154, 16, v155
	v_and_b32_e32 v155, 0xffff0000, v155
	v_pk_fma_f32 v[156:157], v[92:93], v[148:149], v[160:161]
	v_pk_fma_f32 v[160:161], v[90:91], v[154:155], v[164:165]
	v_pk_fma_f32 v[162:163], v[88:89], v[148:149], v[162:163]
	v_pk_fma_f32 v[164:165], v[84:85], v[148:149], v[168:169]
	v_pk_fma_f32 v[148:149], v[80:81], v[148:149], v[150:151]
	v_cndmask_b32_e64 v150, 0, v146, s[4:5]
	v_cndmask_b32_e64 v151, 0, v147, s[4:5]
	v_pk_fma_f32 v[158:159], v[94:95], v[154:155], v[158:159]
	v_pk_fma_f32 v[166:167], v[86:87], v[154:155], v[166:167]
	v_pk_fma_f32 v[152:153], v[82:83], v[154:155], v[152:153]
; DI float bf_lo(unsigned u) { return __uint_as_float(u << 16); }
; DI float bf_hi(unsigned u) { return __uint_as_float(u & 0xffff0000u); }
; DI void conv_unit(int item, const bf16_t* __restrict__ P, bf16_t* __restrict__ Y, const float* __restrict__ cw, const float* __restrict__ cb,
;                   const float* __restrict__ lng, const float* __restrict__ lnb, int lane) {
;     ...
;         for (int tt = 0; tt < 4; ++tt) { acc[tt] = bias;
; #pragma unroll
;             for (int j = 0; j < 31; ++j) { const u32x2 v = r[tt + j]; f32x4 x; x[0] = bf_lo(v.x); x[1] = bf_hi(v.x); x[2] = bf_lo(v.y); x[3] = bf_hi(v.y); acc[tt] += w[j] * x; } }
;         float mean[4], var[4];
; #pragma unroll
;         for (int tt = 0; tt < 4; ++tt) mean[tt] = (acc[tt][0] + acc[tt][1]) + (acc[tt][2] + acc[tt][3]);
	v_lshlrev_b32_e32 v146, 16, v150
	v_and_b32_e32 v147, 0xffff0000, v150
	v_lshlrev_b32_e32 v150, 16, v151
	v_and_b32_e32 v151, 0xffff0000, v151
	v_pk_fma_f32 v[154:155], v[98:99], v[150:151], v[158:159]
	v_pk_fma_f32 v[156:157], v[96:97], v[146:147], v[156:157]
	v_pk_fma_f32 v[158:159], v[92:93], v[146:147], v[162:163]
	v_pk_fma_f32 v[160:161], v[94:95], v[150:151], v[160:161]
	v_pk_fma_f32 v[162:163], v[90:91], v[150:151], v[166:167]
	v_pk_fma_f32 v[164:165], v[88:89], v[146:147], v[164:165]
	v_pk_fma_f32 v[146:147], v[84:85], v[146:147], v[148:149]
	v_pk_fma_f32 v[148:149], v[86:87], v[150:151], v[152:153]
	v_cndmask_b32_e64 v150, 0, v144, s[0:1]
	v_cndmask_b32_e64 v151, 0, v145, s[0:1]
	v_lshlrev_b32_e32 v144, 16, v150
	v_and_b32_e32 v145, 0xffff0000, v150
	v_lshlrev_b32_e32 v150, 16, v151
	v_and_b32_e32 v151, 0xffff0000, v151
	v_pk_fma_f32 v[152:153], v[100:101], v[144:145], v[156:157]
	v_pk_fma_f32 v[154:155], v[102:103], v[150:151], v[154:155]
	v_pk_fma_f32 v[156:157], v[98:99], v[150:151], v[160:161]
	v_pk_fma_f32 v[158:159], v[96:97], v[144:145], v[158:159]
	v_pk_fma_f32 v[160:161], v[92:93], v[144:145], v[164:165]
	v_pk_fma_f32 v[162:163], v[94:95], v[150:151], v[162:163]
	v_pk_fma_f32 v[148:149], v[90:91], v[150:151], v[148:149]
	v_pk_fma_f32 v[144:145], v[88:89], v[144:145], v[146:147]
	v_cndmask_b32_e64 v147, v200, 0, s[72:73]
	v_cndmask_b32_e64 v151, v201, 0, s[72:73]
	v_cndmask_b32_e64 v165, v198, 0, s[72:73]
	v_cndmask_b32_e64 v167, v199, 0, s[72:73]
	v_lshlrev_b32_e32 v146, 16, v147
	v_and_b32_e32 v147, 0xffff0000, v147
	v_lshlrev_b32_e32 v150, 16, v151
	v_and_b32_e32 v151, 0xffff0000, v151
	s_waitcnt vmcnt(5)
	v_cndmask_b32_e64 v168, v202, 0, s[72:73]
	v_cndmask_b32_e64 v169, v203, 0, s[72:73]
	v_pk_fma_f32 v[154:155], v[106:107], v[150:151], v[154:155]
	v_pk_fma_f32 v[152:153], v[104:105], v[146:147], v[152:153]
	v_lshlrev_b32_e32 v164, 16, v165
	v_and_b32_e32 v165, 0xffff0000, v165
	v_lshlrev_b32_e32 v166, 16, v167
	v_and_b32_e32 v167, 0xffff0000, v167
	v_pk_fma_f32 v[158:159], v[100:101], v[146:147], v[158:159]
	v_pk_fma_f32 v[156:157], v[102:103], v[150:151], v[156:157]
	v_pk_fma_f32 v[162:163], v[98:99], v[150:151], v[162:163]
	v_pk_fma_f32 v[160:161], v[96:97], v[146:147], v[160:161]
	v_pk_fma_f32 v[144:145], v[92:93], v[146:147], v[144:145]
	v_pk_fma_f32 v[146:147], v[94:95], v[150:151], v[148:149]
	s_waitcnt vmcnt(4)
	v_cndmask_b32_e64 v170, v204, 0, s[72:73]
	v_cndmask_b32_e64 v171, v205, 0, s[72:73]
	v_pk_fma_f32 v[148:149], v[108:109], v[164:165], v[152:153]
	v_pk_fma_f32 v[150:151], v[110:111], v[166:167], v[154:155]
	v_lshlrev_b32_e32 v152, 16, v168
	v_and_b32_e32 v153, 0xffff0000, v168
	v_lshlrev_b32_e32 v154, 16, v169
	v_and_b32_e32 v155, 0xffff0000, v169
	v_pk_fma_f32 v[156:157], v[106:107], v[166:167], v[156:157]
	v_pk_fma_f32 v[158:159], v[104:105], v[164:165], v[158:159]
	v_pk_fma_f32 v[160:161], v[100:101], v[164:165], v[160:161]
	v_pk_fma_f32 v[162:163], v[102:103], v[166:167], v[162:163]
	v_pk_fma_f32 v[146:147], v[98:99], v[166:167], v[146:147]
	v_pk_fma_f32 v[144:145], v[96:97], v[164:165], v[144:145]
	v_pk_fma_f32 v[150:151], v[114:115], v[154:155], v[150:151]
	v_pk_fma_f32 v[148:149], v[112:113], v[152:153], v[148:149]
	v_lshlrev_b32_e32 v164, 16, v170
	v_and_b32_e32 v165, 0xffff0000, v170
	v_lshlrev_b32_e32 v166, 16, v171
	v_and_b32_e32 v167, 0xffff0000, v171
	v_pk_fma_f32 v[158:159], v[108:109], v[152:153], v[158:159]
	v_pk_fma_f32 v[156:157], v[110:111], v[154:155], v[156:157]
	v_pk_fma_f32 v[162:163], v[106:107], v[154:155], v[162:163]
	v_pk_fma_f32 v[160:161], v[104:105], v[152:153], v[160:161]
	v_pk_fma_f32 v[144:145], v[100:101], v[152:153], v[144:145]
	v_pk_fma_f32 v[146:147], v[102:103], v[154:155], v[146:147]
	s_waitcnt vmcnt(3)
	v_lshlrev_b32_e32 v168, 16, v196
	v_and_b32_e32 v169, 0xffff0000, v196
	v_lshlrev_b32_e32 v170, 16, v197
	v_and_b32_e32 v171, 0xffff0000, v197
	v_pk_fma_f32 v[148:149], v[116:117], v[164:165], v[148:149]
	v_pk_fma_f32 v[150:151], v[118:119], v[166:167], v[150:151]
	v_pk_fma_f32 v[152:153], v[114:115], v[166:167], v[156:157]
	v_pk_fma_f32 v[154:155], v[112:113], v[164:165], v[158:159]
	v_pk_fma_f32 v[160:161], v[108:109], v[164:165], v[160:161]
	v_pk_fma_f32 v[162:163], v[110:111], v[166:167], v[162:163]
	v_pk_fma_f32 v[166:167], v[106:107], v[166:167], v[146:147]
	v_pk_fma_f32 v[164:165], v[104:105], v[164:165], v[144:145]
	s_waitcnt vmcnt(2)
	v_lshlrev_b32_e32 v156, 16, v194
	v_and_b32_e32 v157, 0xffff0000, v194
	v_lshlrev_b32_e32 v158, 16, v195
	v_and_b32_e32 v159, 0xffff0000, v195
	v_pk_fma_f32 v[144:145], v[122:123], v[170:171], v[150:151]
	v_pk_fma_f32 v[146:147], v[120:121], v[168:169], v[148:149]
	v_pk_fma_f32 v[148:149], v[116:117], v[168:169], v[154:155]
	v_pk_fma_f32 v[150:151], v[118:119], v[170:171], v[152:153]
	v_pk_fma_f32 v[152:153], v[114:115], v[170:171], v[162:163]
	v_pk_fma_f32 v[160:161], v[112:113], v[168:169], v[160:161]
	v_pk_fma_f32 v[164:165], v[108:109], v[168:169], v[164:165]
	v_pk_fma_f32 v[166:167], v[110:111], v[170:171], v[166:167]
	s_waitcnt vmcnt(1)
	v_lshlrev_b32_e32 v162, 16, v192
	v_and_b32_e32 v163, 0xffff0000, v192
	v_lshlrev_b32_e32 v172, 16, v193
	v_and_b32_e32 v173, 0xffff0000, v193
	v_pk_fma_f32 v[150:151], v[122:123], v[158:159], v[150:151]
	v_pk_fma_f32 v[154:155], v[120:121], v[156:157], v[148:149]
	v_pk_fma_f32 v[148:149], v[116:117], v[156:157], v[160:161]
	v_pk_fma_f32 v[152:153], v[118:119], v[158:159], v[152:153]
	v_pk_fma_f32 v[158:159], v[114:115], v[158:159], v[166:167]
	v_pk_fma_f32 v[160:161], v[112:113], v[156:157], v[164:165]
	v_pk_mov_b32 v[166:167], v[146:147], v[144:145] op_sel:[1,0]
	v_mov_b32_e32 v168, v146
	v_mov_b32_e32 v169, v145
	s_waitcnt vmcnt(0)
; DI void conv_unit(int item, const bf16_t* __restrict__ P, bf16_t* __restrict__ Y, const float* __restrict__ cw, const float* __restrict__ cb,
;                   const float* __restrict__ lng, const float* __restrict__ lnb, int lane) {
;     ...
;         for (int tt = 0; tt < 4; ++tt) mean[tt] = (acc[tt][0] + acc[tt][1]) + (acc[tt][2] + acc[tt][3]);
; #pragma unroll
;         for (int o = 1; o < 64; o <<= 1) {
; #pragma unroll
;             for (int tt = 0; tt < 4; ++tt) mean[tt] += __shfl_xor(mean[tt], o); }
; #pragma unroll
;         for (int tt = 0; tt < 4; ++tt) { mean[tt] *= (1.0f / 256.0f); acc[tt] -= mean[tt]; var[tt] = (acc[tt][0] * acc[tt][0] + acc[tt][1] * acc[tt][1]) + (acc[tt][2] * acc[tt][2] + acc[tt][3] * acc[tt][3]); }
; #pragma unroll
;         for (int o = 1; o < 64; o <<= 1) {
; #pragma unroll
;             for (int tt = 0; tt < 4; ++tt) var[tt] += __shfl_xor(var[tt], o); }
	v_lshlrev_b32_e32 v164, 16, v138
	v_and_b32_e32 v165, 0xffff0000, v138
	v_lshlrev_b32_e32 v138, 16, v139
	v_and_b32_e32 v139, 0xffff0000, v139
	v_pk_fma_f32 v[152:153], v[122:123], v[172:173], v[152:153]
	v_pk_fma_f32 v[156:157], v[120:121], v[162:163], v[148:149]
	v_pk_fma_f32 v[148:149], v[116:117], v[162:163], v[160:161]
	v_pk_fma_f32 v[158:159], v[118:119], v[172:173], v[158:159]
	v_pk_add_f32 v[160:161], v[166:167], v[168:169]
	v_pk_mov_b32 v[162:163], v[154:155], v[150:151] op_sel:[1,0]
	v_mov_b32_e32 v166, v154
	v_mov_b32_e32 v167, v151
	v_pk_fma_f32 v[138:139], v[122:123], v[138:139], v[158:159]
	v_pk_fma_f32 v[148:149], v[120:121], v[164:165], v[148:149]
	v_add_f32_e32 v164, v160, v161
	v_pk_add_f32 v[158:159], v[162:163], v[166:167]
	v_pk_mov_b32 v[160:161], v[156:157], v[152:153] op_sel:[1,0]
	v_mov_b32_e32 v162, v156
	v_mov_b32_e32 v163, v153
	v_add_f32_e32 v165, v158, v159
	v_pk_add_f32 v[158:159], v[160:161], v[162:163]
	v_pk_mov_b32 v[160:161], v[148:149], v[138:139] op_sel:[1,0]
	v_mov_b32_e32 v162, v148
	v_mov_b32_e32 v163, v139
	ds_bpermute_b32 v166, v206, v164
	v_add_f32_e32 v167, v158, v159
	v_pk_add_f32 v[158:159], v[160:161], v[162:163]
	ds_bpermute_b32 v160, v206, v165
	v_add_f32_e32 v158, v158, v159
	ds_bpermute_b32 v159, v206, v167
	ds_bpermute_b32 v161, v206, v158
	s_waitcnt lgkmcnt(3)
	v_add_f32_e32 v162, v164, v166
	s_waitcnt lgkmcnt(2)
	v_add_f32_e32 v160, v165, v160
	ds_bpermute_b32 v163, v207, v162
	s_waitcnt lgkmcnt(2)
	v_add_f32_e32 v159, v167, v159
	ds_bpermute_b32 v164, v207, v160
	s_waitcnt lgkmcnt(2)
	v_add_f32_e32 v158, v158, v161
	ds_bpermute_b32 v161, v207, v159
	ds_bpermute_b32 v165, v207, v158
	s_waitcnt lgkmcnt(3)
	v_add_f32_e32 v162, v162, v163
	s_waitcnt lgkmcnt(2)
	v_add_f32_e32 v160, v160, v164
	ds_bpermute_b32 v163, v208, v162
	s_waitcnt lgkmcnt(2)
	v_add_f32_e32 v159, v159, v161
	ds_bpermute_b32 v161, v208, v160
	s_waitcnt lgkmcnt(2)
	v_add_f32_e32 v158, v158, v165
	ds_bpermute_b32 v164, v208, v159
	ds_bpermute_b32 v165, v208, v158
	s_waitcnt lgkmcnt(3)
	v_add_f32_e32 v162, v162, v163
	s_waitcnt lgkmcnt(2)
	v_add_f32_e32 v160, v160, v161
	ds_bpermute_b32 v161, v209, v162
	s_waitcnt lgkmcnt(2)
	v_add_f32_e32 v159, v159, v164
	ds_bpermute_b32 v163, v209, v160
	s_waitcnt lgkmcnt(2)
	v_add_f32_e32 v158, v158, v165
	ds_bpermute_b32 v164, v209, v159
	ds_bpermute_b32 v165, v209, v158
	s_waitcnt lgkmcnt(3)
	v_add_f32_e32 v161, v162, v161
	s_waitcnt lgkmcnt(2)
	v_add_f32_e32 v160, v160, v163
	ds_bpermute_b32 v162, v210, v161
	s_waitcnt lgkmcnt(2)
	v_add_f32_e32 v159, v159, v164
	ds_bpermute_b32 v163, v210, v160
	s_waitcnt lgkmcnt(2)
	v_add_f32_e32 v158, v158, v165
	ds_bpermute_b32 v164, v210, v159
	ds_bpermute_b32 v165, v210, v158
	s_waitcnt lgkmcnt(3)
	v_add_f32_e32 v161, v161, v162
	s_waitcnt lgkmcnt(2)
	v_add_f32_e32 v160, v160, v163
	ds_bpermute_b32 v162, v211, v161
	s_waitcnt lgkmcnt(2)
	v_add_f32_e32 v159, v159, v164
	ds_bpermute_b32 v163, v211, v160
	s_waitcnt lgkmcnt(2)
	v_add_f32_e32 v164, v158, v165
	ds_bpermute_b32 v158, v211, v159
	ds_bpermute_b32 v165, v211, v164
	s_waitcnt lgkmcnt(3)
	v_add_f32_e32 v161, v161, v162
	s_waitcnt lgkmcnt(2)
	v_add_f32_e32 v162, v160, v163
	v_fmamk_f32 v147, v161, 0xbb800000, v147
	v_fmac_f32_e32 v146, 0xbb800000, v161
	v_fmamk_f32 v145, v161, 0xbb800000, v145
	v_fmac_f32_e32 v144, 0xbb800000, v161
	s_waitcnt lgkmcnt(1)
	v_add_f32_e32 v166, v159, v158
	v_pk_mul_f32 v[158:159], v[144:145], v[144:145]
	v_pk_mul_f32 v[160:161], v[146:147], v[146:147]
	v_fmamk_f32 v155, v162, 0xbb800000, v155
	v_fmac_f32_e32 v154, 0xbb800000, v162
	v_fmamk_f32 v151, v162, 0xbb800000, v151
	v_fmac_f32_e32 v150, 0xbb800000, v162
	s_waitcnt lgkmcnt(0)
	v_add_f32_e32 v168, v164, v165
	v_pk_mov_b32 v[162:163], v[160:161], v[158:159] op_sel:[1,0]
	v_mov_b32_e32 v161, v159
	v_pk_mul_f32 v[158:159], v[150:151], v[150:151]
	v_pk_mul_f32 v[164:165], v[154:155], v[154:155]
	v_fmamk_f32 v157, v166, 0xbb800000, v157
	v_fmac_f32_e32 v156, 0xbb800000, v166
	v_fmamk_f32 v153, v166, 0xbb800000, v153
	v_fmac_f32_e32 v152, 0xbb800000, v166
	v_pk_add_f32 v[160:161], v[162:163], v[160:161]
	v_pk_mov_b32 v[162:163], v[164:165], v[158:159] op_sel:[1,0]
	v_mov_b32_e32 v165, v159
	v_pk_mul_f32 v[158:159], v[152:153], v[152:153]
	v_pk_mul_f32 v[166:167], v[156:157], v[156:157]
	v_fmamk_f32 v149, v168, 0xbb800000, v149
	v_fmac_f32_e32 v148, 0xbb800000, v168
	v_fmamk_f32 v139, v168, 0xbb800000, v139
	v_fmac_f32_e32 v138, 0xbb800000, v168
	v_add_f32_e32 v168, v160, v161
	v_pk_add_f32 v[160:161], v[162:163], v[164:165]
	v_pk_mov_b32 v[162:163], v[166:167], v[158:159] op_sel:[1,0]
	v_mov_b32_e32 v167, v159
	v_pk_mul_f32 v[158:159], v[138:139], v[138:139]
	v_pk_mul_f32 v[164:165], v[148:149], v[148:149]
	v_add_f32_e32 v169, v160, v161
	v_pk_add_f32 v[160:161], v[162:163], v[166:167]
	v_pk_mov_b32 v[162:163], v[164:165], v[158:159] op_sel:[1,0]
	v_mov_b32_e32 v165, v159
	ds_bpermute_b32 v166, v206, v168
	v_add_f32_e32 v160, v160, v161
	v_pk_add_f32 v[158:159], v[162:163], v[164:165]
	ds_bpermute_b32 v161, v206, v169
	v_add_f32_e32 v158, v158, v159
	ds_bpermute_b32 v159, v206, v160
	ds_bpermute_b32 v162, v206, v158
	s_waitcnt lgkmcnt(3)
	v_add_f32_e32 v163, v168, v166
	s_waitcnt lgkmcnt(2)
	v_add_f32_e32 v161, v169, v161
	ds_bpermute_b32 v164, v207, v163
	s_waitcnt lgkmcnt(2)
	v_add_f32_e32 v159, v160, v159
	ds_bpermute_b32 v160, v207, v161
	s_waitcnt lgkmcnt(2)
	v_add_f32_e32 v158, v158, v162
	ds_bpermute_b32 v162, v207, v159
	s_waitcnt lgkmcnt(2)
	v_add_f32_e32 v163, v163, v164
	ds_bpermute_b32 v165, v207, v158
	s_waitcnt lgkmcnt(2)
	v_add_f32_e32 v160, v161, v160
	ds_bpermute_b32 v161, v208, v163
	s_waitcnt lgkmcnt(2)
; DI void conv_unit(int item, const bf16_t* __restrict__ P, bf16_t* __restrict__ Y, const float* __restrict__ cw, const float* __restrict__ cb,
;                   const float* __restrict__ lng, const float* __restrict__ lnb, int lane) {
;     ...
;         for (int o = 1; o < 64; o <<= 1) {
; #pragma unroll
;             for (int tt = 0; tt < 4; ++tt) var[tt] += __shfl_xor(var[tt], o); }
; #pragma unroll
;         for (int tt = 0; tt < 4; ++tt) {
;             const float rs = 1.0f / sqrtf(var[tt] * (1.0f / 256.0f) + 1e-6f);
	v_add_f32_e32 v159, v159, v162
	ds_bpermute_b32 v162, v208, v160
	ds_bpermute_b32 v164, v208, v159
	s_waitcnt lgkmcnt(3)
	v_add_f32_e32 v158, v158, v165
	s_waitcnt lgkmcnt(2)
	v_add_f32_e32 v161, v163, v161
	ds_bpermute_b32 v165, v208, v158
	s_waitcnt lgkmcnt(2)
	v_add_f32_e32 v160, v160, v162
	ds_bpermute_b32 v162, v209, v161
	ds_bpermute_b32 v163, v209, v160
	s_waitcnt lgkmcnt(3)
	v_add_f32_e32 v159, v159, v164
	ds_bpermute_b32 v164, v209, v159
	s_waitcnt lgkmcnt(3)
	v_add_f32_e32 v158, v158, v165
	s_waitcnt lgkmcnt(2)
	v_add_f32_e32 v161, v161, v162
	ds_bpermute_b32 v165, v209, v158
	ds_bpermute_b32 v162, v210, v161
	s_waitcnt lgkmcnt(3)
	v_add_f32_e32 v160, v160, v163
	ds_bpermute_b32 v163, v210, v160
	s_waitcnt lgkmcnt(3)
	v_add_f32_e32 v159, v159, v164
	ds_bpermute_b32 v164, v210, v159
	s_waitcnt lgkmcnt(3)
	v_add_f32_e32 v158, v158, v165
	s_waitcnt lgkmcnt(2)
	v_add_f32_e32 v161, v161, v162
	ds_bpermute_b32 v165, v210, v158
	ds_bpermute_b32 v162, v211, v161
	s_waitcnt lgkmcnt(3)
	v_add_f32_e32 v160, v160, v163
	ds_bpermute_b32 v163, v211, v160
	s_waitcnt lgkmcnt(3)
	v_add_f32_e32 v159, v159, v164
	ds_bpermute_b32 v164, v211, v159
	s_waitcnt lgkmcnt(3)
	v_add_f32_e32 v158, v158, v165
	s_waitcnt lgkmcnt(2)
	v_add_f32_e32 v161, v161, v162
	ds_bpermute_b32 v165, v211, v158
	v_fmamk_f32 v161, v161, 0x3b800000, v212
	s_waitcnt lgkmcnt(2)
	v_add_f32_e32 v160, v160, v163
	v_mul_f32_e32 v162, 0x4f800000, v161
	v_cmp_gt_f32_e32 vcc, s59, v161
	v_fmamk_f32 v160, v160, 0x3b800000, v212
	s_waitcnt lgkmcnt(1)
	v_add_f32_e32 v159, v159, v164
	v_cndmask_b32_e32 v161, v161, v162, vcc
	v_mul_f32_e32 v162, 0x4f800000, v160
	v_cmp_gt_f32_e64 s[0:1], s59, v160
	v_sqrt_f32_e32 v163, v161
	v_fmamk_f32 v159, v159, 0x3b800000, v212
	v_cndmask_b32_e64 v160, v160, v162, s[0:1]
	s_waitcnt lgkmcnt(0)
	v_add_f32_e32 v158, v158, v165
	v_mul_f32_e32 v162, 0x4f800000, v159
	v_cmp_gt_f32_e64 s[4:5], s59, v159
	v_sqrt_f32_e32 v164, v160
	v_fmamk_f32 v158, v158, 0x3b800000, v212
	v_cndmask_b32_e64 v159, v159, v162, s[4:5]
	v_mul_f32_e32 v162, 0x4f800000, v158
	v_cmp_gt_f32_e64 s[6:7], s59, v158
	v_sqrt_f32_e32 v165, v159
	v_add_u32_e32 v166, -1, v163
	v_cndmask_b32_e64 v158, v158, v162, s[6:7]
	v_add_u32_e32 v167, 1, v163
	v_fma_f32 v168, -v166, v163, v161
	v_sqrt_f32_e32 v162, v158
	v_fma_f32 v169, -v167, v163, v161
	v_add_u32_e32 v170, -1, v164
	v_cmp_ge_f32_e64 s[8:9], 0, v168
	v_add_u32_e32 v171, 1, v164
	v_fma_f32 v168, -v171, v164, v160
	v_cndmask_b32_e64 v163, v163, v166, s[8:9]
	v_fma_f32 v166, -v170, v164, v160
	v_cmp_lt_f32_e64 s[8:9], 0, v169
	v_add_u32_e32 v172, -1, v165
	v_add_u32_e32 v173, 1, v165
	v_cndmask_b32_e64 v163, v163, v167, s[8:9]
	v_cmp_ge_f32_e64 s[8:9], 0, v166
	v_fma_f32 v166, -v172, v165, v159
	v_fma_f32 v167, -v173, v165, v159
	v_cndmask_b32_e64 v164, v164, v170, s[8:9]
	v_cmp_lt_f32_e64 s[8:9], 0, v168
	v_add_u32_e32 v168, -1, v162
	v_add_u32_e32 v169, 1, v162
	v_cndmask_b32_e64 v164, v164, v171, s[8:9]
	v_cmp_ge_f32_e64 s[8:9], 0, v166
	v_mul_f32_e32 v170, 0x37800000, v163
	v_fma_f32 v166, -v168, v162, v158
	v_cndmask_b32_e64 v165, v165, v172, s[8:9]
	v_cmp_lt_f32_e64 s[8:9], 0, v167
	v_fma_f32 v167, -v169, v162, v158
	v_cndmask_b32_e32 v163, v163, v170, vcc
	v_cndmask_b32_e64 v165, v165, v173, s[8:9]
	v_cmp_ge_f32_e32 vcc, 0, v166
	v_cmp_class_f32_e64 s[8:9], v161, v213
	v_mul_f32_e32 v170, 0x37800000, v164
	v_cndmask_b32_e32 v162, v162, v168, vcc
	v_cmp_lt_f32_e32 vcc, 0, v167
	v_cndmask_b32_e64 v161, v163, v161, s[8:9]
	v_cndmask_b32_e64 v163, v164, v170, s[0:1]
	v_cmp_class_f32_e64 s[0:1], v160, v213
	v_mul_f32_e32 v164, 0x37800000, v165
	v_cndmask_b32_e32 v162, v162, v169, vcc
	v_div_scale_f32 v166, s[8:9], v161, v161, 1.0
	v_cndmask_b32_e64 v160, v163, v160, s[0:1]
	v_cndmask_b32_e64 v163, v165, v164, s[4:5]
	v_cmp_class_f32_e64 s[0:1], v159, v213
	v_mul_f32_e32 v164, 0x37800000, v162
	v_rcp_f32_e32 v165, v166
	v_div_scale_f32 v168, s[4:5], v160, v160, 1.0
	v_cndmask_b32_e64 v159, v163, v159, s[0:1]
	v_cndmask_b32_e64 v162, v162, v164, s[6:7]
	v_cmp_class_f32_e64 s[0:1], v158, v213
	v_rcp_f32_e32 v163, v168
	v_div_scale_f32 v164, s[6:7], v159, v159, 1.0
	v_cndmask_b32_e64 v162, v162, v158, s[0:1]
	v_rcp_f32_e32 v171, v164
	v_div_scale_f32 v172, s[0:1], v162, v162, 1.0
	v_rcp_f32_e32 v174, v172
	v_fma_f32 v158, -v166, v165, 1.0
	v_div_scale_f32 v167, vcc, 1.0, v161, 1.0
	v_fmac_f32_e32 v165, v158, v165
	v_fma_f32 v158, -v168, v163, 1.0
	v_mul_f32_e32 v175, v167, v165
	v_div_scale_f32 v169, s[4:5], 1.0, v160, 1.0
	v_fmac_f32_e32 v163, v158, v163
	v_fma_f32 v158, -v164, v171, 1.0
	v_fma_f32 v176, -v166, v175, v167
	v_div_scale_f32 v170, s[6:7], 1.0, v159, 1.0
	v_mul_f32_e32 v177, v169, v163
	v_fmac_f32_e32 v171, v158, v171
	v_fma_f32 v158, -v172, v174, 1.0
	v_fmac_f32_e32 v175, v176, v165
	v_div_scale_f32 v173, s[0:1], 1.0, v162, 1.0
	v_fma_f32 v176, -v168, v177, v169
	v_mul_f32_e32 v178, v170, v171
; __device__ __forceinline__ f32x4 silu4(const f32x4 g) { f32x4 o; o[0] = g[0] * sigmoid_f(g[0]); o[1] = g[1] * sigmoid_f(g[1]); o[2] = g[2] * sigmoid_f(g[2]); o[3] = g[3] * sigmoid_f(g[3]); return o; }
; DI void conv_unit(int item, const bf16_t* __restrict__ P, bf16_t* __restrict__ Y, const float* __restrict__ cw, const float* __restrict__ cb,
;                   const float* __restrict__ lng, const float* __restrict__ lnb, int lane) {
;     ...
;     for (int ps = 0; ps < 4; ++ps) {
;     ...
;         for (int tt = 0; tt < 4; ++tt) {
;             const float rs = 1.0f / sqrtf(var[tt] * (1.0f / 256.0f) + 1e-6f);
;             const f32x4 y = pg8::silu4(acc[tt] * rs * g4 + b4);
;             u32x2 o; o.x = pk2(y[0], y[1]); o.y = pk2(y[2], y[3]);
;             *(u32x2*)(Y + (size_t)(tok + tt) * DM + Y_CV + 4 * lane) = o;
;         }
;     }
	v_fmac_f32_e32 v174, v158, v174
	v_fma_f32 v158, -v166, v175, v167
	v_fmac_f32_e32 v177, v176, v163
	v_fma_f32 v166, -v164, v178, v170
	v_mul_f32_e32 v167, v173, v174
	v_div_fmas_f32 v158, v158, v165, v175
	v_fma_f32 v165, -v168, v177, v169
	v_fmac_f32_e32 v178, v166, v171
	v_fma_f32 v166, -v172, v167, v173
	v_div_fixup_f32 v158, v158, v161, 1.0
	s_mov_b64 vcc, s[4:5]
	v_div_fmas_f32 v161, v165, v163, v177
	v_fma_f32 v163, -v164, v178, v170
	v_fmac_f32_e32 v167, v166, v174
	v_pk_mul_f32 v[146:147], v[146:147], v[158:159] op_sel_hi:[1,0]
	s_mov_b64 vcc, s[6:7]
	v_pk_mul_f32 v[144:145], v[144:145], v[158:159] op_sel_hi:[1,0]
	v_div_fixup_f32 v158, v161, v160, 1.0
	v_div_fmas_f32 v160, v163, v171, v178
	v_fma_f32 v161, -v172, v167, v173
	v_pk_fma_f32 v[146:147], v[128:129], v[146:147], v[132:133]
	s_mov_b64 vcc, s[0:1]
	v_pk_mul_f32 v[154:155], v[154:155], v[158:159] op_sel_hi:[1,0]
	v_pk_mul_f32 v[150:151], v[150:151], v[158:159] op_sel_hi:[1,0]
	v_div_fixup_f32 v158, v160, v159, 1.0
	v_div_fmas_f32 v159, v161, v174, v167
	v_mul_f32_e32 v160, 0xbfb8aa3b, v146
	v_pk_mul_f32 v[156:157], v[156:157], v[158:159] op_sel_hi:[1,0]
	v_pk_mul_f32 v[152:153], v[152:153], v[158:159] op_sel_hi:[1,0]
	v_div_fixup_f32 v158, v159, v162, 1.0
	v_exp_f32_e32 v159, v160
	v_pk_fma_f32 v[144:145], v[130:131], v[144:145], v[134:135]
	v_mul_f32_e32 v161, 0xbfb8aa3b, v147
	v_mul_f32_e32 v163, 0xbfb8aa3b, v144
	v_mul_f32_e32 v164, 0xbfb8aa3b, v145
	v_pk_fma_f32 v[150:151], v[130:131], v[150:151], v[134:135]
	v_pk_fma_f32 v[154:155], v[128:129], v[154:155], v[132:133]
	v_exp_f32_e32 v160, v161
	v_exp_f32_e32 v161, v163
	v_exp_f32_e32 v162, v164
	v_mul_f32_e32 v163, 0xbfb8aa3b, v154
	v_mul_f32_e32 v164, 0xbfb8aa3b, v155
	v_mul_f32_e32 v165, 0xbfb8aa3b, v150
	v_mul_f32_e32 v166, 0xbfb8aa3b, v151
	v_pk_fma_f32 v[156:157], v[128:129], v[156:157], v[132:133]
	v_pk_mul_f32 v[148:149], v[148:149], v[158:159] op_sel_hi:[1,0]
	v_pk_mul_f32 v[138:139], v[138:139], v[158:159] op_sel_hi:[1,0]
	v_pk_fma_f32 v[152:153], v[130:131], v[152:153], v[134:135]
	v_exp_f32_e32 v158, v163
	v_exp_f32_e32 v163, v164
	v_exp_f32_e32 v164, v165
	v_exp_f32_e32 v165, v166
	v_mul_f32_e32 v166, 0xbfb8aa3b, v156
	v_mul_f32_e32 v167, 0xbfb8aa3b, v157
	v_pk_fma_f32 v[138:139], v[130:131], v[138:139], v[134:135]
	v_pk_fma_f32 v[148:149], v[128:129], v[148:149], v[132:133]
	v_mul_f32_e32 v168, 0xbfb8aa3b, v152
	v_mul_f32_e32 v169, 0xbfb8aa3b, v153
	v_exp_f32_e32 v166, v166
	v_exp_f32_e32 v167, v167
	v_mul_f32_e32 v170, 0xbfb8aa3b, v148
	v_mul_f32_e32 v171, 0xbfb8aa3b, v149
	v_mul_f32_e32 v172, 0xbfb8aa3b, v138
	v_mul_f32_e32 v173, 0xbfb8aa3b, v139
	v_exp_f32_e32 v168, v168
	v_exp_f32_e32 v169, v169
	v_exp_f32_e32 v170, v170
	v_exp_f32_e32 v171, v171
	v_exp_f32_e32 v172, v172
	v_exp_f32_e32 v173, v173
	v_add_f32_e32 v159, 1.0, v159
	v_add_f32_e32 v160, 1.0, v160
	v_add_f32_e32 v161, 1.0, v161
	v_add_f32_e32 v162, 1.0, v162
	v_rcp_f32_e32 v159, v159
	v_rcp_f32_e32 v160, v160
	v_rcp_f32_e32 v161, v161
	v_rcp_f32_e32 v162, v162
	v_add_f32_e32 v158, 1.0, v158
	v_add_f32_e32 v163, 1.0, v163
	v_add_f32_e32 v164, 1.0, v164
	v_add_f32_e32 v165, 1.0, v165
	v_rcp_f32_e32 v158, v158
	v_rcp_f32_e32 v163, v163
	v_rcp_f32_e32 v164, v164
	v_rcp_f32_e32 v165, v165
	v_add_f32_e32 v166, 1.0, v166
	v_add_f32_e32 v167, 1.0, v167
	v_add_f32_e32 v168, 1.0, v168
	v_add_f32_e32 v169, 1.0, v169
	v_rcp_f32_e32 v166, v166
	v_rcp_f32_e32 v167, v167
	v_add_f32_e32 v170, 1.0, v170
	v_add_f32_e32 v171, 1.0, v171
	v_add_f32_e32 v172, 1.0, v172
	v_add_f32_e32 v173, 1.0, v173
	s_add_i32 s3, s3, 4
	v_rcp_f32_e32 v168, v168
	v_rcp_f32_e32 v169, v169
	v_rcp_f32_e32 v170, v170
	v_rcp_f32_e32 v171, v171
	v_rcp_f32_e32 v172, v172
	v_rcp_f32_e32 v173, v173
	s_add_u32 s66, s66, 0x2000
	v_mul_f32_e32 v146, v146, v159
	v_mul_f32_e32 v147, v147, v160
	v_mul_f32_e32 v159, v144, v161
	v_mul_f32_e32 v145, v145, v162
	s_addc_u32 s67, s67, 0
	v_cvt_pk_bf16_f32 v144, v146, v147
	v_cvt_pk_bf16_f32 v145, v159, v145
	v_mul_f32_e32 v146, v154, v158
	v_mul_f32_e32 v147, v155, v163
	v_mul_f32_e32 v150, v150, v164
	v_mul_f32_e32 v151, v151, v165
	s_add_u32 s68, s68, 0x4200
	global_store_dwordx2 v[140:141], v[144:145], off offset:-4096
	v_cvt_pk_bf16_f32 v144, v146, v147
	v_cvt_pk_bf16_f32 v145, v150, v151
	v_mul_f32_e32 v146, v156, v166
	v_mul_f32_e32 v147, v157, v167
	s_addc_u32 s69, s69, 0
	v_mul_f32_e32 v150, v152, v168
	v_mul_f32_e32 v151, v153, v169
	global_store_dwordx2 v[142:143], v[144:145], off offset:2048
	v_cvt_pk_bf16_f32 v142, v146, v147
	v_mul_f32_e32 v144, v148, v170
	v_mul_f32_e32 v145, v149, v171
	v_mul_f32_e32 v146, v138, v172
	v_mul_f32_e32 v139, v139, v173
	s_cmp_eq_u32 s3, s100
	v_cvt_pk_bf16_f32 v143, v150, v151
	v_cvt_pk_bf16_f32 v138, v144, v145
	v_cvt_pk_bf16_f32 v139, v146, v139
	global_store_dwordx2 v[140:141], v[142:143], off
	global_store_dwordx2 v[140:141], v[138:139], off offset:2048
	s_cbranch_scc0 .LBB0_703

; DI void conv_unit(int item, const bf16_t* __restrict__ P, bf16_t* __restrict__ Y, const float* __restrict__ cw, const float* __restrict__ cb,
;                   const float* __restrict__ lng, const float* __restrict__ lnb, int lane) {
;     const int tok0 = item * 16;
;     f32x4 w[31];
; #pragma unroll
;     for (int j = 0; j < 31; ++j) w[j] = *(const f32x4*)(cw + j * 256 + 4 * lane);
;     const f32x4 bias = *(const f32x4*)(cb + 4 * lane), g4 = *(const f32x4*)(lng + 4 * lane), b4 = *(const f32x4*)(lnb + 4 * lane);
; #pragma unroll 1
;     for (int ps = 0; ps < 4; ++ps) {
;         const int tok = tok0 + 4 * ps, tl = tok & (SEQ - 1);
;         const bf16_t* src = P + (size_t)tok * PW + P_CV + 4 * lane;
;     ...
;                 const int bid = (G % 8 == 0) ? ((int)blockIdx.x % 8) * (G / 8) + (int)blockIdx.x / 8 : (int)blockIdx.x;
;                 if (wave < 2) { int ln = lane; asm volatile("" : "+v"(ln) :: "memory"); DO_R1(ret1_unit(bid * 2 + wave, T, (float*)(ws + WS_G), ln, lds + wave * 16384)); }
;                 { int ln = lane; asm volatile("" : "+v"(ln) :: "memory"); DO_CV(conv_unit(bid * 8 + wave, P, Y, a.in[6] + l * 31 * 256, a.in[7] + l * 256, a.in[8] + l * 256, a.in[9] + l * 256, ln)); }
.LBB0_1584:
	v_mov_b32_e32 v0, v251
	s_mov_b64 s[0:1], 0x7c00
	v_lshlrev_b32_e32 v136, 2, v0
	v_ashrrev_i32_e32 v137, 31, v136
	v_lshlrev_b64 v[132:133], 2, v[136:137]
	v_lshl_add_u64 v[112:113], s[84:85], 0, v[132:133]
	s_waitcnt vmcnt(0)
	v_add_co_u32_e32 v18, vcc, 0x7000, v112
	v_lshl_add_u64 v[16:17], v[112:113], 0, s[0:1]
	s_nop 0
	v_addc_co_u32_e32 v19, vcc, 0, v113, vcc
	v_add_co_u32_e32 v32, vcc, 0x8000, v112
	v_readlane_b32 s12, v255, 4
	s_nop 0
	v_addc_co_u32_e32 v33, vcc, 0, v113, vcc
	v_add_co_u32_e32 v48, vcc, 0x9000, v112
	s_waitcnt lgkmcnt(0)
	global_load_dwordx4 v[0:3], v[16:17], off offset:1024
	global_load_dwordx4 v[4:7], v[16:17], off offset:2048
	global_load_dwordx4 v[8:11], v[18:19], off offset:3072
	global_load_dwordx4 v[12:15], v[16:17], off offset:3072
	v_addc_co_u32_e32 v49, vcc, 0, v113, vcc
	v_add_co_u32_e32 v64, vcc, 0xa000, v112
	global_load_dwordx4 v[16:19], v[32:33], off offset:3072
	global_load_dwordx4 v[20:23], v[48:49], off
	global_load_dwordx4 v[24:27], v[48:49], off offset:1024
	global_load_dwordx4 v[28:31], v[48:49], off offset:2048
	v_addc_co_u32_e32 v65, vcc, 0, v113, vcc
	v_add_co_u32_e32 v80, vcc, 0xb000, v112
	global_load_dwordx4 v[32:35], v[48:49], off offset:3072
	global_load_dwordx4 v[36:39], v[64:65], off
	global_load_dwordx4 v[40:43], v[64:65], off offset:1024
	global_load_dwordx4 v[44:47], v[64:65], off offset:2048
	v_addc_co_u32_e32 v81, vcc, 0, v113, vcc
	v_add_co_u32_e32 v96, vcc, 0xc000, v112
	global_load_dwordx4 v[48:51], v[64:65], off offset:3072
	global_load_dwordx4 v[52:55], v[80:81], off
	global_load_dwordx4 v[56:59], v[80:81], off offset:1024
	global_load_dwordx4 v[60:63], v[80:81], off offset:2048
	v_addc_co_u32_e32 v97, vcc, 0, v113, vcc
	v_add_co_u32_e32 v114, vcc, 0xd000, v112
	global_load_dwordx4 v[64:67], v[80:81], off offset:3072
	global_load_dwordx4 v[68:71], v[96:97], off
	global_load_dwordx4 v[72:75], v[96:97], off offset:1024
	global_load_dwordx4 v[76:79], v[96:97], off offset:2048
	v_addc_co_u32_e32 v115, vcc, 0, v113, vcc
	v_add_co_u32_e32 v116, vcc, 0xe000, v112
	global_load_dwordx4 v[80:83], v[96:97], off offset:3072
	global_load_dwordx4 v[84:87], v[114:115], off
	global_load_dwordx4 v[88:91], v[114:115], off offset:1024
	global_load_dwordx4 v[92:95], v[114:115], off offset:2048
	v_addc_co_u32_e32 v117, vcc, 0, v113, vcc
	v_add_co_u32_e32 v120, vcc, 0xf000, v112
	global_load_dwordx4 v[96:99], v[114:115], off offset:3072
	global_load_dwordx4 v[100:103], v[116:117], off
	global_load_dwordx4 v[104:107], v[116:117], off offset:1024
	global_load_dwordx4 v[108:111], v[116:117], off offset:2048
	v_addc_co_u32_e32 v121, vcc, 0, v113, vcc
	v_readlane_b32 s13, v255, 5
	v_readlane_b32 s14, v255, 6
	v_readlane_b32 s15, v255, 7
	global_load_dwordx4 v[112:115], v[116:117], off offset:3072
	s_nop 0
	global_load_dwordx4 v[116:119], v[120:121], off
	s_nop 0
	global_load_dwordx4 v[120:123], v[120:121], off offset:1024
	v_lshl_add_u64 v[124:125], s[86:87], 0, v[132:133]
	v_lshl_add_u64 v[128:129], s[12:13], 0, v[132:133]
	v_lshl_add_u64 v[132:133], s[14:15], 0, v[132:133]
	global_load_dwordx4 v[124:127], v[124:125], off offset:1024
	v_mbcnt_lo_u32_b32 v138, -1, 0
	global_load_dwordx4 v[128:131], v[128:129], off offset:1024
	v_mbcnt_hi_u32_b32 v138, -1, v138
	global_load_dwordx4 v[132:135], v[132:133], off offset:1024
	v_and_b32_e32 v139, 64, v138
	v_add_u32_e32 v139, 64, v139
	v_xor_b32_e32 v140, 1, v138
	v_cmp_lt_i32_e32 vcc, v140, v139
	s_lshl_b32 s0, s8, 7
	s_and_b32 s101, s96, 3
	s_lshl_b32 s101, s101, 3
	s_mov_b32 s1, 0x70604c38
	s_cmp_lt_u32 s96, 4
	s_cmov_b32 s1, 0x24100800
	s_mov_b32 s100, 0x10101414
	s_cmov_b32 s100, 0x14140808
	s_lshr_b32 s1, s1, s101
	s_lshr_b32 s100, s100, s101
	s_and_b32 s1, s1, 0xff
	s_and_b32 s100, s100, 0xff
	v_cndmask_b32_e32 v140, v138, v140, vcc
	v_lshlrev_b32_e32 v206, 2, v140
	v_xor_b32_e32 v140, 2, v138
	v_cmp_lt_i32_e32 vcc, v140, v139
	s_add_i32 s56, s1, s0
	s_ashr_i32 s57, s56, 31
	v_cndmask_b32_e32 v140, v138, v140, vcc
	v_lshlrev_b32_e32 v207, 2, v140
	v_xor_b32_e32 v140, 4, v138
	v_cmp_lt_i32_e32 vcc, v140, v139
	s_lshl_b64 s[0:1], s[56:57], 11
	s_add_u32 s58, s90, s0
	v_cndmask_b32_e32 v140, v138, v140, vcc
	v_lshlrev_b32_e32 v208, 2, v140
	v_xor_b32_e32 v140, 8, v138
	v_cmp_lt_i32_e32 vcc, v140, v139
	s_addc_u32 s59, s91, s1
	s_mul_i32 s1, s56, 0x1080
	v_cndmask_b32_e32 v140, v138, v140, vcc
	v_lshlrev_b32_e32 v209, 2, v140
	v_xor_b32_e32 v140, 16, v138
	v_cmp_lt_i32_e32 vcc, v140, v139
	s_mul_hi_i32 s0, s56, 0x1080
	s_add_u32 s64, s90, s1
	v_cndmask_b32_e32 v140, v138, v140, vcc
	v_lshlrev_b32_e32 v210, 2, v140
	v_xor_b32_e32 v140, 32, v138
	v_cmp_lt_i32_e32 vcc, v140, v139
	s_mov_b64 s[72:73], s[46:47]
	s_mov_b32 s3, 0
	v_cndmask_b32_e32 v138, v138, v140, vcc
	v_lshlrev_b32_e32 v211, 2, v138
	v_lshlrev_b64 v[136:137], 1, v[136:137]
	s_addc_u32 s65, s91, s0
	s_mov_b32 s33, 0x12500000
	s_mov_b32 s57, 0x12501000
	s_mov_b32 s60, 0x12502000
	s_mov_b32 s61, 0x12503000
	v_mov_b32_e32 v212, 0x358637bd
	s_mov_b32 s62, 0xf800000
	v_mov_b32_e32 v213, 0x260
	s_mov_b32 s63, 0xa400000
	s_mov_b32 s70, 0xa401000
	v_readlane_b32 s16, v255, 8
	v_readlane_b32 s17, v255, 9
	v_readlane_b32 s18, v255, 10
	v_readlane_b32 s19, v255, 11
	v_readlane_b32 s20, v255, 12
	v_readlane_b32 s21, v255, 13
	v_readlane_b32 s22, v255, 14
	v_readlane_b32 s23, v255, 15
	v_readlane_b32 s24, v255, 16
	v_readlane_b32 s25, v255, 17
	v_readlane_b32 s26, v255, 18
	v_readlane_b32 s27, v255, 19
; DI void conv_unit(int item, const bf16_t* __restrict__ P, bf16_t* __restrict__ Y, const float* __restrict__ cw, const float* __restrict__ cb,
;                   const float* __restrict__ lng, const float* __restrict__ lnb, int lane) {
;     ...
;     for (int ps = 0; ps < 4; ++ps) {
;         const int tok = tok0 + 4 * ps, tl = tok & (SEQ - 1);
;         const bf16_t* src = P + (size_t)tok * PW + P_CV + 4 * lane;
;         u32x2 r[34];
; #pragma unroll
;         for (int i = 0; i < 34; ++i) { const bool ok = (tl - 30 + i) >= 0; const u32x2 v = *(const u32x2*)(src + (ok ? (i - 30) * PW : 0)); r[i].x = ok ? v.x : 0u; r[i].y = ok ? v.y : 0u; }
.LBB0_1585:
	s_add_i32 s0, s56, s3
	s_and_b32 s66, s0, 0x1ffc
	v_lshl_add_u64 v[140:141], s[58:59], 0, v[136:137]
	s_cmp_gt_u32 s66, 29
	v_add_co_u32_e32 v142, vcc, s63, v140
	s_cselect_b64 s[54:55], -1, 0
	s_nop 0
	v_addc_co_u32_e32 v143, vcc, 0, v141, vcc
	s_and_b64 s[0:1], s[54:55], exec
	v_lshl_add_u64 v[138:139], s[64:65], 0, v[136:137]
	v_add_co_u32_e32 v140, vcc, s70, v140
	s_cselect_b32 s1, -1, 0
	s_cselect_b32 s0, 0xfffe1100, 0
	s_cmp_gt_u32 s66, 28
	v_addc_co_u32_e32 v141, vcc, 0, v141, vcc
	v_lshl_add_u64 v[144:145], v[138:139], 0, s[0:1]
	s_cselect_b64 s[52:53], -1, 0
	v_add_co_u32_e32 v144, vcc, 0x12500000, v144
	s_and_b64 s[0:1], s[52:53], exec
	s_nop 0
	v_addc_co_u32_e32 v145, vcc, 0, v145, vcc
	s_cselect_b32 s1, -1, 0
	s_cselect_b32 s0, 0xfffe2180, 0
	s_cmp_gt_u32 s66, 27
	global_load_dwordx2 v[194:195], v[144:145], off
	v_lshl_add_u64 v[144:145], v[138:139], 0, s[0:1]
	s_cselect_b64 s[50:51], -1, 0
	v_add_co_u32_e32 v144, vcc, s33, v144
	s_and_b64 s[0:1], s[50:51], exec
	s_nop 0
	v_addc_co_u32_e32 v145, vcc, 0, v145, vcc
	s_cselect_b32 s1, -1, 0
	s_cselect_b32 s0, 0xfffe3200, 0
	s_cmp_gt_u32 s66, 26
	global_load_dwordx2 v[192:193], v[144:145], off
	v_lshl_add_u64 v[144:145], v[138:139], 0, s[0:1]
	s_cselect_b64 s[48:49], -1, 0
	v_add_co_u32_e32 v144, vcc, s33, v144
	s_and_b64 s[0:1], s[48:49], exec
	s_nop 0
	v_addc_co_u32_e32 v145, vcc, 0, v145, vcc
	s_cselect_b32 s1, -1, 0
	s_cselect_b32 s0, 0xfffe4280, 0
	s_cmp_gt_u32 s66, 25
	global_load_dwordx2 v[190:191], v[144:145], off
	v_lshl_add_u64 v[144:145], v[138:139], 0, s[0:1]
	s_cselect_b64 s[46:47], -1, 0
	v_add_co_u32_e32 v144, vcc, s33, v144
	s_and_b64 s[0:1], s[46:47], exec
	s_nop 0
	v_addc_co_u32_e32 v145, vcc, 0, v145, vcc
	s_cselect_b32 s1, -1, 0
	s_cselect_b32 s0, 0xfffe5300, 0
	s_cmp_gt_u32 s66, 24
	global_load_dwordx2 v[188:189], v[144:145], off
	v_lshl_add_u64 v[144:145], v[138:139], 0, s[0:1]
	s_cselect_b64 s[44:45], -1, 0
	v_add_co_u32_e32 v144, vcc, s33, v144
	s_and_b64 s[0:1], s[44:45], exec
	s_nop 0
	v_addc_co_u32_e32 v145, vcc, 0, v145, vcc
	s_cselect_b32 s1, -1, 0
	s_cselect_b32 s0, 0xfffe6380, 0
	s_cmp_gt_u32 s66, 23
	global_load_dwordx2 v[186:187], v[144:145], off
	v_lshl_add_u64 v[144:145], v[138:139], 0, s[0:1]
	s_cselect_b64 s[42:43], -1, 0
	v_add_co_u32_e32 v144, vcc, s33, v144
	s_and_b64 s[0:1], s[42:43], exec
	s_nop 0
	v_addc_co_u32_e32 v145, vcc, 0, v145, vcc
	s_cselect_b32 s1, -1, 0
	s_cselect_b32 s0, 0xfffe7400, 0
	s_cmp_gt_u32 s66, 22
	global_load_dwordx2 v[184:185], v[144:145], off
	v_lshl_add_u64 v[144:145], v[138:139], 0, s[0:1]
	s_cselect_b64 s[40:41], -1, 0
	v_add_co_u32_e32 v144, vcc, s33, v144
	s_and_b64 s[0:1], s[40:41], exec
	s_nop 0
	v_addc_co_u32_e32 v145, vcc, 0, v145, vcc
	s_cselect_b32 s1, -1, 0
	s_cselect_b32 s0, 0xfffe8480, 0
	s_cmp_gt_u32 s66, 21
	global_load_dwordx2 v[182:183], v[144:145], off
	v_lshl_add_u64 v[144:145], v[138:139], 0, s[0:1]
	s_cselect_b64 s[38:39], -1, 0
	v_add_co_u32_e32 v144, vcc, s33, v144
	s_and_b64 s[0:1], s[38:39], exec
	s_nop 0
	v_addc_co_u32_e32 v145, vcc, 0, v145, vcc
	s_cselect_b32 s1, -1, 0
	s_cselect_b32 s0, 0xfffe9500, 0
	s_cmp_gt_u32 s66, 20
	global_load_dwordx2 v[180:181], v[144:145], off
	v_lshl_add_u64 v[144:145], v[138:139], 0, s[0:1]
	s_cselect_b64 s[36:37], -1, 0
	v_add_co_u32_e32 v144, vcc, s33, v144
	s_and_b64 s[0:1], s[36:37], exec
	s_nop 0
	v_addc_co_u32_e32 v145, vcc, 0, v145, vcc
	s_cselect_b32 s1, -1, 0
	s_cselect_b32 s0, 0xfffea580, 0
	s_cmp_gt_u32 s66, 19
	global_load_dwordx2 v[178:179], v[144:145], off
	v_lshl_add_u64 v[144:145], v[138:139], 0, s[0:1]
	s_cselect_b64 s[34:35], -1, 0
	v_add_co_u32_e32 v144, vcc, s33, v144
	s_and_b64 s[0:1], s[34:35], exec
	s_nop 0
	v_addc_co_u32_e32 v145, vcc, 0, v145, vcc
	s_cselect_b32 s1, -1, 0
	s_cselect_b32 s0, 0xfffeb600, 0
	s_cmp_gt_u32 s66, 18
	global_load_dwordx2 v[176:177], v[144:145], off
	v_lshl_add_u64 v[144:145], v[138:139], 0, s[0:1]
	s_cselect_b64 s[30:31], -1, 0
	v_add_co_u32_e32 v144, vcc, s33, v144
	s_and_b64 s[0:1], s[30:31], exec
	s_nop 0
	v_addc_co_u32_e32 v145, vcc, 0, v145, vcc
	s_cselect_b32 s1, -1, 0
	s_cselect_b32 s0, 0xfffec680, 0
	s_cmp_gt_u32 s66, 17
	global_load_dwordx2 v[174:175], v[144:145], off
	v_lshl_add_u64 v[144:145], v[138:139], 0, s[0:1]
	s_cselect_b64 s[28:29], -1, 0
	v_add_co_u32_e32 v144, vcc, s33, v144
	s_and_b64 s[0:1], s[28:29], exec
	s_nop 0
	v_addc_co_u32_e32 v145, vcc, 0, v145, vcc
	s_cselect_b32 s1, -1, 0
	s_cselect_b32 s0, 0xfffed700, 0
	s_cmp_gt_u32 s66, 16
	global_load_dwordx2 v[172:173], v[144:145], off
	v_lshl_add_u64 v[144:145], v[138:139], 0, s[0:1]
	s_cselect_b64 s[26:27], -1, 0
	v_add_co_u32_e32 v144, vcc, s33, v144
	s_and_b64 s[0:1], s[26:27], exec
	s_nop 0
	v_addc_co_u32_e32 v145, vcc, 0, v145, vcc
	s_cselect_b32 s1, -1, 0
	s_cselect_b32 s0, 0xfffee780, 0
	s_cmp_gt_u32 s66, 15
	global_load_dwordx2 v[170:171], v[144:145], off
	v_lshl_add_u64 v[144:145], v[138:139], 0, s[0:1]
	s_cselect_b64 s[24:25], -1, 0
	v_add_co_u32_e32 v144, vcc, s33, v144
	s_and_b64 s[0:1], s[24:25], exec
	s_nop 0
	v_addc_co_u32_e32 v145, vcc, 0, v145, vcc
	s_cselect_b32 s1, -1, 0
	s_cselect_b32 s0, 0xfffef800, 0
	s_cmp_gt_u32 s66, 14
	global_load_dwordx2 v[168:169], v[144:145], off
	v_lshl_add_u64 v[144:145], v[138:139], 0, s[0:1]
	s_cselect_b64 s[22:23], -1, 0
	v_add_co_u32_e32 v144, vcc, s33, v144
	s_and_b64 s[0:1], s[22:23], exec
	s_nop 0
	v_addc_co_u32_e32 v145, vcc, 0, v145, vcc
	s_cselect_b32 s1, -1, 0
	s_cselect_b32 s0, 0xffff0880, 0
	s_cmp_gt_u32 s66, 13
	global_load_dwordx2 v[166:167], v[144:145], off
	v_lshl_add_u64 v[144:145], v[138:139], 0, s[0:1]
	s_cselect_b64 s[20:21], -1, 0
	v_add_co_u32_e32 v144, vcc, s33, v144
; DI float bf_lo(unsigned u) { return __uint_as_float(u << 16); }
; DI float bf_hi(unsigned u) { return __uint_as_float(u & 0xffff0000u); }
; DI void conv_unit(int item, const bf16_t* __restrict__ P, bf16_t* __restrict__ Y, const float* __restrict__ cw, const float* __restrict__ cb,
;                   const float* __restrict__ lng, const float* __restrict__ lnb, int lane) {
;     ...
;         for (int i = 0; i < 34; ++i) { const bool ok = (tl - 30 + i) >= 0; const u32x2 v = *(const u32x2*)(src + (ok ? (i - 30) * PW : 0)); r[i].x = ok ? v.x : 0u; r[i].y = ok ? v.y : 0u; }
;         f32x4 acc[4];
; #pragma unroll
;         for (int tt = 0; tt < 4; ++tt) { acc[tt] = bias;
; #pragma unroll
;             for (int j = 0; j < 31; ++j) { const u32x2 v = r[tt + j]; f32x4 x; x[0] = bf_lo(v.x); x[1] = bf_hi(v.x); x[2] = bf_lo(v.y); x[3] = bf_hi(v.y); acc[tt] += w[j] * x; } }
	s_and_b64 s[0:1], s[20:21], exec
	s_nop 0
	v_addc_co_u32_e32 v145, vcc, 0, v145, vcc
	s_cselect_b32 s1, -1, 0
	s_cselect_b32 s0, 0xffff1900, 0
	s_cmp_gt_u32 s66, 12
	global_load_dwordx2 v[164:165], v[144:145], off
	v_lshl_add_u64 v[144:145], v[138:139], 0, s[0:1]
	s_cselect_b64 s[18:19], -1, 0
	v_add_co_u32_e32 v144, vcc, s33, v144
	s_and_b64 s[0:1], s[18:19], exec
	s_nop 0
	v_addc_co_u32_e32 v145, vcc, 0, v145, vcc
	s_cselect_b32 s1, -1, 0
	s_cselect_b32 s0, 0xffff2980, 0
	s_cmp_gt_u32 s66, 11
	global_load_dwordx2 v[162:163], v[144:145], off
	v_lshl_add_u64 v[144:145], v[138:139], 0, s[0:1]
	s_cselect_b64 s[16:17], -1, 0
	v_add_co_u32_e32 v144, vcc, s33, v144
	s_and_b64 s[0:1], s[16:17], exec
	s_nop 0
	v_addc_co_u32_e32 v145, vcc, 0, v145, vcc
	s_cselect_b32 s1, -1, 0
	s_cselect_b32 s0, 0xffff3a00, 0
	s_cmp_gt_u32 s66, 10
	global_load_dwordx2 v[160:161], v[144:145], off
	v_lshl_add_u64 v[144:145], v[138:139], 0, s[0:1]
	s_cselect_b64 s[14:15], -1, 0
	v_add_co_u32_e32 v144, vcc, s33, v144
	s_and_b64 s[0:1], s[14:15], exec
	s_nop 0
	v_addc_co_u32_e32 v145, vcc, 0, v145, vcc
	s_cselect_b32 s1, -1, 0
	s_cselect_b32 s0, 0xffff4a80, 0
	s_cmp_gt_u32 s66, 9
	global_load_dwordx2 v[158:159], v[144:145], off
	v_lshl_add_u64 v[144:145], v[138:139], 0, s[0:1]
	s_cselect_b64 s[12:13], -1, 0
	v_add_co_u32_e32 v144, vcc, s33, v144
	s_and_b64 s[0:1], s[12:13], exec
	s_nop 0
	v_addc_co_u32_e32 v145, vcc, 0, v145, vcc
	s_cselect_b32 s1, -1, 0
	s_cselect_b32 s0, 0xffff5b00, 0
	s_cmp_gt_u32 s66, 8
	global_load_dwordx2 v[156:157], v[144:145], off
	v_lshl_add_u64 v[144:145], v[138:139], 0, s[0:1]
	s_cselect_b64 s[10:11], -1, 0
	v_add_co_u32_e32 v144, vcc, s33, v144
	s_and_b64 s[0:1], s[10:11], exec
	s_nop 0
	v_addc_co_u32_e32 v145, vcc, 0, v145, vcc
	s_cselect_b32 s1, -1, 0
	s_cselect_b32 s0, 0xffff6b80, 0
	s_cmp_gt_u32 s66, 7
	global_load_dwordx2 v[154:155], v[144:145], off
	v_lshl_add_u64 v[144:145], v[138:139], 0, s[0:1]
	s_cselect_b64 s[8:9], -1, 0
	v_add_co_u32_e32 v144, vcc, s33, v144
	s_and_b64 s[0:1], s[8:9], exec
	s_nop 0
	v_addc_co_u32_e32 v145, vcc, 0, v145, vcc
	s_cselect_b32 s1, -1, 0
	s_cselect_b32 s0, 0xffff7c00, 0
	s_cmp_gt_u32 s66, 6
	global_load_dwordx2 v[152:153], v[144:145], off
	v_lshl_add_u64 v[144:145], v[138:139], 0, s[0:1]
	s_cselect_b64 s[6:7], -1, 0
	v_add_co_u32_e32 v144, vcc, s33, v144
	s_and_b64 s[0:1], s[6:7], exec
	s_nop 0
	v_addc_co_u32_e32 v145, vcc, 0, v145, vcc
	s_cselect_b32 s1, -1, 0
	s_cselect_b32 s0, 0xffff8c80, 0
	s_cmp_gt_u32 s66, 5
	global_load_dwordx2 v[150:151], v[144:145], off
	v_lshl_add_u64 v[144:145], v[138:139], 0, s[0:1]
	s_cselect_b64 s[4:5], -1, 0
	v_add_co_u32_e32 v144, vcc, s33, v144
	s_and_b64 s[0:1], s[4:5], exec
	s_nop 0
	v_addc_co_u32_e32 v145, vcc, 0, v145, vcc
	s_cselect_b32 s1, -1, 0
	s_cselect_b32 s0, 0xffff9d00, 0
	s_cmp_gt_u32 s66, 4
	global_load_dwordx2 v[148:149], v[144:145], off
	v_lshl_add_u64 v[144:145], v[138:139], 0, s[0:1]
	s_cselect_b64 s[0:1], -1, 0
	s_and_b64 s[68:69], s[0:1], exec
	v_add_co_u32_e32 v144, vcc, s33, v144
	s_cselect_b32 s69, -1, 0
	s_cselect_b32 s68, 0xffffad80, 0
	s_cmp_eq_u32 s66, 0
	v_addc_co_u32_e32 v145, vcc, 0, v145, vcc
	s_cselect_b64 s[66:67], -1, 0
	global_load_dwordx2 v[146:147], v[144:145], off
	v_lshl_add_u64 v[144:145], v[138:139], 0, s[68:69]
	s_and_b64 s[68:69], s[66:67], exec
	v_add_co_u32_e32 v144, vcc, s33, v144
	s_cselect_b32 s69, 0, -1
	s_cselect_b32 s68, 0, 0xffffbe00
	v_addc_co_u32_e32 v145, vcc, 0, v145, vcc
	v_lshl_add_u64 v[196:197], v[138:139], 0, s[68:69]
	s_cselect_b32 s68, 0, 0xffffce80
	v_add_co_u32_e32 v196, vcc, s33, v196
	v_lshl_add_u64 v[198:199], v[138:139], 0, s[68:69]
	s_nop 0
	v_addc_co_u32_e32 v197, vcc, 0, v197, vcc
	s_cselect_b32 s68, 0, 0xffffef80
	v_add_co_u32_e32 v198, vcc, s33, v198
	v_lshl_add_u64 v[202:203], s[68:69], 1, v[138:139]
	s_nop 0
	v_addc_co_u32_e32 v199, vcc, 0, v199, vcc
	v_add_co_u32_e32 v202, vcc, s33, v202
	v_lshl_add_u64 v[204:205], v[138:139], 0, s[68:69]
	s_nop 0
	v_addc_co_u32_e32 v203, vcc, 0, v203, vcc
	global_load_dwordx2 v[144:145], v[144:145], off
	s_nop 0
	global_load_dwordx2 v[200:201], v[196:197], off
	s_nop 0
	global_load_dwordx2 v[198:199], v[198:199], off
	v_add_co_u32_e32 v196, vcc, s33, v204
	s_waitcnt vmcnt(27)
	v_cndmask_b32_e64 v204, 0, v194, s[54:55]
	v_addc_co_u32_e32 v197, vcc, 0, v205, vcc
	v_add_co_u32_e32 v194, vcc, s33, v138
	v_cndmask_b32_e64 v215, 0, v195, s[54:55]
	s_nop 0
	v_addc_co_u32_e32 v195, vcc, 0, v139, vcc
	global_load_dwordx2 v[202:203], v[202:203], off
	v_add_co_u32_e32 v214, vcc, s57, v138
	v_lshlrev_b32_e32 v218, 16, v215
	v_and_b32_e32 v219, 0xffff0000, v215
	v_addc_co_u32_e32 v215, vcc, 0, v139, vcc
	v_lshlrev_b32_e32 v216, 16, v204
	v_and_b32_e32 v217, 0xffff0000, v204
	global_load_dwordx2 v[204:205], v[196:197], off
	s_nop 0
	global_load_dwordx2 v[196:197], v[194:195], off
	v_add_co_u32_e32 v220, vcc, s60, v138
	global_load_dwordx2 v[194:195], v[214:215], off offset:128
	s_nop 0
	v_addc_co_u32_e32 v221, vcc, 0, v139, vcc
	v_add_co_u32_e32 v138, vcc, s61, v138
	s_waitcnt vmcnt(30)
	v_cndmask_b32_e64 v192, 0, v192, s[52:53]
	v_cndmask_b32_e64 v193, 0, v193, s[52:53]
	v_addc_co_u32_e32 v139, vcc, 0, v139, vcc
	v_lshlrev_b32_e32 v214, 16, v192
	v_and_b32_e32 v215, 0xffff0000, v192
	v_lshlrev_b32_e32 v222, 16, v193
	v_and_b32_e32 v223, 0xffff0000, v193
	global_load_dwordx2 v[192:193], v[220:221], off offset:256
	s_nop 0
	global_load_dwordx2 v[138:139], v[138:139], off offset:384
	v_pk_fma_f32 v[218:219], v[10:11], v[218:219], v[126:127]
	v_pk_fma_f32 v[216:217], v[8:9], v[216:217], v[124:125]
	v_pk_fma_f32 v[218:219], v[2:3], v[222:223], v[218:219]
	v_pk_fma_f32 v[220:221], v[10:11], v[222:223], v[126:127]
	s_waitcnt vmcnt(31)
; DI float bf_lo(unsigned u) { return __uint_as_float(u << 16); }
; DI float bf_hi(unsigned u) { return __uint_as_float(u & 0xffff0000u); }
; DI void conv_unit(int item, const bf16_t* __restrict__ P, bf16_t* __restrict__ Y, const float* __restrict__ cw, const float* __restrict__ cb,
;                   const float* __restrict__ lng, const float* __restrict__ lnb, int lane) {
;     ...
;         for (int tt = 0; tt < 4; ++tt) { acc[tt] = bias;
; #pragma unroll
;             for (int j = 0; j < 31; ++j) { const u32x2 v = r[tt + j]; f32x4 x; x[0] = bf_lo(v.x); x[1] = bf_hi(v.x); x[2] = bf_lo(v.y); x[3] = bf_hi(v.y); acc[tt] += w[j] * x; } }
	v_cndmask_b32_e64 v222, 0, v190, s[50:51]
	v_cndmask_b32_e64 v223, 0, v191, s[50:51]
	v_pk_fma_f32 v[216:217], v[0:1], v[214:215], v[216:217]
	v_pk_fma_f32 v[214:215], v[8:9], v[214:215], v[124:125]
	v_lshlrev_b32_e32 v190, 16, v222
	v_and_b32_e32 v191, 0xffff0000, v222
	v_lshlrev_b32_e32 v222, 16, v223
	v_and_b32_e32 v223, 0xffff0000, v223
	s_waitcnt vmcnt(30)
	v_cndmask_b32_e64 v224, 0, v188, s[48:49]
	v_cndmask_b32_e64 v225, 0, v189, s[48:49]
	v_pk_fma_f32 v[218:219], v[6:7], v[222:223], v[218:219]
	v_pk_fma_f32 v[216:217], v[4:5], v[190:191], v[216:217]
	v_pk_fma_f32 v[214:215], v[0:1], v[190:191], v[214:215]
	v_pk_fma_f32 v[220:221], v[2:3], v[222:223], v[220:221]
	v_pk_fma_f32 v[222:223], v[10:11], v[222:223], v[126:127]
	v_pk_fma_f32 v[190:191], v[8:9], v[190:191], v[124:125]
	v_lshlrev_b32_e32 v188, 16, v224
	v_and_b32_e32 v189, 0xffff0000, v224
	v_lshlrev_b32_e32 v224, 16, v225
	v_and_b32_e32 v225, 0xffff0000, v225
	s_waitcnt vmcnt(29)
	v_cndmask_b32_e64 v226, 0, v186, s[46:47]
	v_cndmask_b32_e64 v227, 0, v187, s[46:47]
	v_pk_fma_f32 v[216:217], v[12:13], v[188:189], v[216:217]
	v_pk_fma_f32 v[218:219], v[14:15], v[224:225], v[218:219]
	v_pk_fma_f32 v[220:221], v[6:7], v[224:225], v[220:221]
	v_pk_fma_f32 v[214:215], v[4:5], v[188:189], v[214:215]
	v_pk_fma_f32 v[190:191], v[0:1], v[188:189], v[190:191]
	v_pk_fma_f32 v[222:223], v[2:3], v[224:225], v[222:223]
	v_pk_fma_f32 v[224:225], v[10:11], v[224:225], v[126:127]
	v_pk_fma_f32 v[188:189], v[8:9], v[188:189], v[124:125]
	v_lshlrev_b32_e32 v186, 16, v226
	v_and_b32_e32 v187, 0xffff0000, v226
	v_lshlrev_b32_e32 v226, 16, v227
	v_and_b32_e32 v227, 0xffff0000, v227
	v_pk_fma_f32 v[216:217], v[16:17], v[186:187], v[216:217]
	v_pk_fma_f32 v[214:215], v[12:13], v[186:187], v[214:215]
	v_pk_fma_f32 v[190:191], v[4:5], v[186:187], v[190:191]
	v_pk_fma_f32 v[186:187], v[0:1], v[186:187], v[188:189]
	v_pk_fma_f32 v[188:189], v[2:3], v[226:227], v[224:225]
	s_waitcnt vmcnt(28)
	v_cndmask_b32_e64 v224, 0, v184, s[44:45]
	v_cndmask_b32_e64 v225, 0, v185, s[44:45]
	v_lshlrev_b32_e32 v184, 16, v224
	v_and_b32_e32 v185, 0xffff0000, v224
	v_pk_fma_f32 v[218:219], v[18:19], v[226:227], v[218:219]
	v_pk_fma_f32 v[220:221], v[14:15], v[226:227], v[220:221]
	v_pk_fma_f32 v[222:223], v[6:7], v[226:227], v[222:223]
	v_lshlrev_b32_e32 v224, 16, v225
	v_and_b32_e32 v225, 0xffff0000, v225
	v_pk_fma_f32 v[216:217], v[20:21], v[184:185], v[216:217]
	v_pk_fma_f32 v[214:215], v[16:17], v[184:185], v[214:215]
	v_pk_fma_f32 v[190:191], v[12:13], v[184:185], v[190:191]
	v_pk_fma_f32 v[184:185], v[4:5], v[184:185], v[186:187]
	s_waitcnt vmcnt(27)
	v_cndmask_b32_e64 v186, 0, v182, s[42:43]
	v_cndmask_b32_e64 v187, 0, v183, s[42:43]
	v_pk_fma_f32 v[218:219], v[22:23], v[224:225], v[218:219]
	v_pk_fma_f32 v[220:221], v[18:19], v[224:225], v[220:221]
	v_pk_fma_f32 v[222:223], v[14:15], v[224:225], v[222:223]
	v_pk_fma_f32 v[188:189], v[6:7], v[224:225], v[188:189]
	v_lshlrev_b32_e32 v182, 16, v186
	v_and_b32_e32 v183, 0xffff0000, v186
	v_lshlrev_b32_e32 v186, 16, v187
	v_and_b32_e32 v187, 0xffff0000, v187
	v_pk_fma_f32 v[218:219], v[26:27], v[186:187], v[218:219]
	v_pk_fma_f32 v[216:217], v[24:25], v[182:183], v[216:217]
	v_pk_fma_f32 v[214:215], v[20:21], v[182:183], v[214:215]
	v_pk_fma_f32 v[220:221], v[22:23], v[186:187], v[220:221]
	v_pk_fma_f32 v[222:223], v[18:19], v[186:187], v[222:223]
	v_pk_fma_f32 v[190:191], v[16:17], v[182:183], v[190:191]
	v_pk_fma_f32 v[182:183], v[12:13], v[182:183], v[184:185]
	v_pk_fma_f32 v[184:185], v[14:15], v[186:187], v[188:189]
	s_waitcnt vmcnt(26)
	v_cndmask_b32_e64 v186, 0, v180, s[40:41]
	v_cndmask_b32_e64 v187, 0, v181, s[40:41]
	v_lshlrev_b32_e32 v180, 16, v186
	v_and_b32_e32 v181, 0xffff0000, v186
	v_lshlrev_b32_e32 v186, 16, v187
	v_and_b32_e32 v187, 0xffff0000, v187
	v_pk_fma_f32 v[188:189], v[28:29], v[180:181], v[216:217]
	v_pk_fma_f32 v[214:215], v[24:25], v[180:181], v[214:215]
	v_pk_fma_f32 v[190:191], v[20:21], v[180:181], v[190:191]
	v_pk_fma_f32 v[180:181], v[16:17], v[180:181], v[182:183]
	s_waitcnt vmcnt(25)
	v_cndmask_b32_e64 v182, 0, v178, s[38:39]
	v_cndmask_b32_e64 v183, 0, v179, s[38:39]
	v_pk_fma_f32 v[216:217], v[30:31], v[186:187], v[218:219]
	v_pk_fma_f32 v[218:219], v[26:27], v[186:187], v[220:221]
	v_pk_fma_f32 v[220:221], v[22:23], v[186:187], v[222:223]
	v_pk_fma_f32 v[184:185], v[18:19], v[186:187], v[184:185]
	v_lshlrev_b32_e32 v178, 16, v182
	v_and_b32_e32 v179, 0xffff0000, v182
	v_lshlrev_b32_e32 v182, 16, v183
	v_and_b32_e32 v183, 0xffff0000, v183
	v_pk_fma_f32 v[186:187], v[34:35], v[182:183], v[216:217]
	v_pk_fma_f32 v[188:189], v[32:33], v[178:179], v[188:189]
	v_pk_fma_f32 v[214:215], v[28:29], v[178:179], v[214:215]
	v_pk_fma_f32 v[216:217], v[30:31], v[182:183], v[218:219]
	v_pk_fma_f32 v[218:219], v[26:27], v[182:183], v[220:221]
	v_pk_fma_f32 v[190:191], v[24:25], v[178:179], v[190:191]
	v_pk_fma_f32 v[178:179], v[20:21], v[178:179], v[180:181]
	v_pk_fma_f32 v[180:181], v[22:23], v[182:183], v[184:185]
	s_waitcnt vmcnt(24)
	v_cndmask_b32_e64 v182, 0, v176, s[36:37]
	v_cndmask_b32_e64 v183, 0, v177, s[36:37]
	v_lshlrev_b32_e32 v176, 16, v182
	v_and_b32_e32 v177, 0xffff0000, v182
	v_lshlrev_b32_e32 v182, 16, v183
	v_and_b32_e32 v183, 0xffff0000, v183
	v_pk_fma_f32 v[184:185], v[36:37], v[176:177], v[188:189]
	v_pk_fma_f32 v[214:215], v[32:33], v[176:177], v[214:215]
	v_pk_fma_f32 v[190:191], v[28:29], v[176:177], v[190:191]
	v_pk_fma_f32 v[176:177], v[24:25], v[176:177], v[178:179]
	s_waitcnt vmcnt(23)
; DI float bf_lo(unsigned u) { return __uint_as_float(u << 16); }
; DI float bf_hi(unsigned u) { return __uint_as_float(u & 0xffff0000u); }
; DI void conv_unit(int item, const bf16_t* __restrict__ P, bf16_t* __restrict__ Y, const float* __restrict__ cw, const float* __restrict__ cb,
;                   const float* __restrict__ lng, const float* __restrict__ lnb, int lane) {
;     ...
;         for (int tt = 0; tt < 4; ++tt) { acc[tt] = bias;
; #pragma unroll
;             for (int j = 0; j < 31; ++j) { const u32x2 v = r[tt + j]; f32x4 x; x[0] = bf_lo(v.x); x[1] = bf_hi(v.x); x[2] = bf_lo(v.y); x[3] = bf_hi(v.y); acc[tt] += w[j] * x; } }
	v_cndmask_b32_e64 v178, 0, v174, s[34:35]
	v_cndmask_b32_e64 v179, 0, v175, s[34:35]
	v_pk_fma_f32 v[186:187], v[38:39], v[182:183], v[186:187]
	v_pk_fma_f32 v[188:189], v[34:35], v[182:183], v[216:217]
	v_pk_fma_f32 v[216:217], v[30:31], v[182:183], v[218:219]
	v_pk_fma_f32 v[180:181], v[26:27], v[182:183], v[180:181]
	v_lshlrev_b32_e32 v174, 16, v178
	v_and_b32_e32 v175, 0xffff0000, v178
	v_lshlrev_b32_e32 v178, 16, v179
	v_and_b32_e32 v179, 0xffff0000, v179
	v_pk_fma_f32 v[182:183], v[42:43], v[178:179], v[186:187]
	v_pk_fma_f32 v[184:185], v[40:41], v[174:175], v[184:185]
	v_pk_fma_f32 v[186:187], v[36:37], v[174:175], v[214:215]
	v_pk_fma_f32 v[188:189], v[38:39], v[178:179], v[188:189]
	v_pk_fma_f32 v[214:215], v[34:35], v[178:179], v[216:217]
	v_pk_fma_f32 v[190:191], v[32:33], v[174:175], v[190:191]
	v_pk_fma_f32 v[174:175], v[28:29], v[174:175], v[176:177]
	v_pk_fma_f32 v[176:177], v[30:31], v[178:179], v[180:181]
	s_waitcnt vmcnt(22)
	v_cndmask_b32_e64 v178, 0, v172, s[30:31]
	v_cndmask_b32_e64 v179, 0, v173, s[30:31]
	v_lshlrev_b32_e32 v172, 16, v178
	v_and_b32_e32 v173, 0xffff0000, v178
	v_lshlrev_b32_e32 v178, 16, v179
	v_and_b32_e32 v179, 0xffff0000, v179
	v_pk_fma_f32 v[180:181], v[44:45], v[172:173], v[184:185]
	v_pk_fma_f32 v[184:185], v[42:43], v[178:179], v[188:189]
	v_pk_fma_f32 v[186:187], v[40:41], v[172:173], v[186:187]
	v_pk_fma_f32 v[188:189], v[36:37], v[172:173], v[190:191]
	v_pk_fma_f32 v[172:173], v[32:33], v[172:173], v[174:175]
	s_waitcnt vmcnt(21)
	v_cndmask_b32_e64 v174, 0, v170, s[28:29]
	v_cndmask_b32_e64 v175, 0, v171, s[28:29]
	v_pk_fma_f32 v[182:183], v[46:47], v[178:179], v[182:183]
	v_pk_fma_f32 v[190:191], v[38:39], v[178:179], v[214:215]
	v_pk_fma_f32 v[176:177], v[34:35], v[178:179], v[176:177]
	v_lshlrev_b32_e32 v170, 16, v174
	v_and_b32_e32 v171, 0xffff0000, v174
	v_lshlrev_b32_e32 v174, 16, v175
	v_and_b32_e32 v175, 0xffff0000, v175
	v_pk_fma_f32 v[178:179], v[50:51], v[174:175], v[182:183]
	v_pk_fma_f32 v[180:181], v[48:49], v[170:171], v[180:181]
	v_pk_fma_f32 v[182:183], v[44:45], v[170:171], v[186:187]
	v_pk_fma_f32 v[184:185], v[46:47], v[174:175], v[184:185]
	v_pk_fma_f32 v[186:187], v[42:43], v[174:175], v[190:191]
	v_pk_fma_f32 v[188:189], v[40:41], v[170:171], v[188:189]
	v_pk_fma_f32 v[170:171], v[36:37], v[170:171], v[172:173]
	v_pk_fma_f32 v[172:173], v[38:39], v[174:175], v[176:177]
	s_waitcnt vmcnt(20)
	v_cndmask_b32_e64 v174, 0, v168, s[26:27]
	v_cndmask_b32_e64 v175, 0, v169, s[26:27]
	v_lshlrev_b32_e32 v168, 16, v174
	v_and_b32_e32 v169, 0xffff0000, v174
	v_lshlrev_b32_e32 v174, 16, v175
	v_and_b32_e32 v175, 0xffff0000, v175
	v_pk_fma_f32 v[176:177], v[52:53], v[168:169], v[180:181]
	v_pk_fma_f32 v[180:181], v[50:51], v[174:175], v[184:185]
	v_pk_fma_f32 v[182:183], v[48:49], v[168:169], v[182:183]
	v_pk_fma_f32 v[184:185], v[44:45], v[168:169], v[188:189]
	v_pk_fma_f32 v[168:169], v[40:41], v[168:169], v[170:171]
	s_waitcnt vmcnt(19)
	v_cndmask_b32_e64 v170, 0, v166, s[24:25]
	v_cndmask_b32_e64 v171, 0, v167, s[24:25]
	v_pk_fma_f32 v[178:179], v[54:55], v[174:175], v[178:179]
	v_pk_fma_f32 v[186:187], v[46:47], v[174:175], v[186:187]
	v_pk_fma_f32 v[172:173], v[42:43], v[174:175], v[172:173]
	v_lshlrev_b32_e32 v166, 16, v170
	v_and_b32_e32 v167, 0xffff0000, v170
	v_lshlrev_b32_e32 v170, 16, v171
	v_and_b32_e32 v171, 0xffff0000, v171
	v_pk_fma_f32 v[174:175], v[58:59], v[170:171], v[178:179]
	v_pk_fma_f32 v[176:177], v[56:57], v[166:167], v[176:177]
	v_pk_fma_f32 v[178:179], v[52:53], v[166:167], v[182:183]
	v_pk_fma_f32 v[180:181], v[54:55], v[170:171], v[180:181]
	v_pk_fma_f32 v[182:183], v[50:51], v[170:171], v[186:187]
	v_pk_fma_f32 v[184:185], v[48:49], v[166:167], v[184:185]
	v_pk_fma_f32 v[166:167], v[44:45], v[166:167], v[168:169]
	v_pk_fma_f32 v[168:169], v[46:47], v[170:171], v[172:173]
	s_waitcnt vmcnt(18)
	v_cndmask_b32_e64 v170, 0, v164, s[22:23]
	v_cndmask_b32_e64 v171, 0, v165, s[22:23]
	v_lshlrev_b32_e32 v164, 16, v170
	v_and_b32_e32 v165, 0xffff0000, v170
	v_lshlrev_b32_e32 v170, 16, v171
	v_and_b32_e32 v171, 0xffff0000, v171
	v_pk_fma_f32 v[172:173], v[60:61], v[164:165], v[176:177]
	v_pk_fma_f32 v[176:177], v[58:59], v[170:171], v[180:181]
	v_pk_fma_f32 v[178:179], v[56:57], v[164:165], v[178:179]
	v_pk_fma_f32 v[180:181], v[52:53], v[164:165], v[184:185]
	v_pk_fma_f32 v[164:165], v[48:49], v[164:165], v[166:167]
	s_waitcnt vmcnt(17)
	v_cndmask_b32_e64 v166, 0, v162, s[20:21]
	v_cndmask_b32_e64 v167, 0, v163, s[20:21]
	v_pk_fma_f32 v[174:175], v[62:63], v[170:171], v[174:175]
	v_pk_fma_f32 v[182:183], v[54:55], v[170:171], v[182:183]
	v_pk_fma_f32 v[168:169], v[50:51], v[170:171], v[168:169]
	v_lshlrev_b32_e32 v162, 16, v166
	v_and_b32_e32 v163, 0xffff0000, v166
	v_lshlrev_b32_e32 v166, 16, v167
	v_and_b32_e32 v167, 0xffff0000, v167
	v_pk_fma_f32 v[170:171], v[66:67], v[166:167], v[174:175]
	v_pk_fma_f32 v[172:173], v[64:65], v[162:163], v[172:173]
	v_pk_fma_f32 v[174:175], v[60:61], v[162:163], v[178:179]
	v_pk_fma_f32 v[176:177], v[62:63], v[166:167], v[176:177]
	v_pk_fma_f32 v[178:179], v[58:59], v[166:167], v[182:183]
	v_pk_fma_f32 v[180:181], v[56:57], v[162:163], v[180:181]
	v_pk_fma_f32 v[162:163], v[52:53], v[162:163], v[164:165]
	v_pk_fma_f32 v[164:165], v[54:55], v[166:167], v[168:169]
	s_waitcnt vmcnt(16)
	v_cndmask_b32_e64 v166, 0, v160, s[18:19]
	v_cndmask_b32_e64 v167, 0, v161, s[18:19]
	v_lshlrev_b32_e32 v160, 16, v166
	v_and_b32_e32 v161, 0xffff0000, v166
	v_lshlrev_b32_e32 v166, 16, v167
	v_and_b32_e32 v167, 0xffff0000, v167
	v_pk_fma_f32 v[168:169], v[68:69], v[160:161], v[172:173]
	v_pk_fma_f32 v[172:173], v[66:67], v[166:167], v[176:177]
	v_pk_fma_f32 v[174:175], v[64:65], v[160:161], v[174:175]
	v_pk_fma_f32 v[176:177], v[60:61], v[160:161], v[180:181]
	v_pk_fma_f32 v[160:161], v[56:57], v[160:161], v[162:163]
	s_waitcnt vmcnt(15)
; DI float bf_lo(unsigned u) { return __uint_as_float(u << 16); }
; DI float bf_hi(unsigned u) { return __uint_as_float(u & 0xffff0000u); }
; DI void conv_unit(int item, const bf16_t* __restrict__ P, bf16_t* __restrict__ Y, const float* __restrict__ cw, const float* __restrict__ cb,
;                   const float* __restrict__ lng, const float* __restrict__ lnb, int lane) {
;     ...
;         for (int tt = 0; tt < 4; ++tt) { acc[tt] = bias;
; #pragma unroll
;             for (int j = 0; j < 31; ++j) { const u32x2 v = r[tt + j]; f32x4 x; x[0] = bf_lo(v.x); x[1] = bf_hi(v.x); x[2] = bf_lo(v.y); x[3] = bf_hi(v.y); acc[tt] += w[j] * x; } }
	v_cndmask_b32_e64 v162, 0, v158, s[16:17]
	v_cndmask_b32_e64 v163, 0, v159, s[16:17]
	v_pk_fma_f32 v[170:171], v[70:71], v[166:167], v[170:171]
	v_pk_fma_f32 v[178:179], v[62:63], v[166:167], v[178:179]
	v_pk_fma_f32 v[164:165], v[58:59], v[166:167], v[164:165]
	v_lshlrev_b32_e32 v158, 16, v162
	v_and_b32_e32 v159, 0xffff0000, v162
	v_lshlrev_b32_e32 v162, 16, v163
	v_and_b32_e32 v163, 0xffff0000, v163
	v_pk_fma_f32 v[166:167], v[74:75], v[162:163], v[170:171]
	v_pk_fma_f32 v[168:169], v[72:73], v[158:159], v[168:169]
	v_pk_fma_f32 v[170:171], v[68:69], v[158:159], v[174:175]
	v_pk_fma_f32 v[172:173], v[70:71], v[162:163], v[172:173]
	v_pk_fma_f32 v[174:175], v[66:67], v[162:163], v[178:179]
	v_pk_fma_f32 v[176:177], v[64:65], v[158:159], v[176:177]
	v_pk_fma_f32 v[158:159], v[60:61], v[158:159], v[160:161]
	v_pk_fma_f32 v[160:161], v[62:63], v[162:163], v[164:165]
	s_waitcnt vmcnt(14)
	v_cndmask_b32_e64 v162, 0, v156, s[14:15]
	v_cndmask_b32_e64 v163, 0, v157, s[14:15]
	v_lshlrev_b32_e32 v156, 16, v162
	v_and_b32_e32 v157, 0xffff0000, v162
	v_lshlrev_b32_e32 v162, 16, v163
	v_and_b32_e32 v163, 0xffff0000, v163
	v_pk_fma_f32 v[164:165], v[76:77], v[156:157], v[168:169]
	v_pk_fma_f32 v[168:169], v[74:75], v[162:163], v[172:173]
	v_pk_fma_f32 v[170:171], v[72:73], v[156:157], v[170:171]
	v_pk_fma_f32 v[172:173], v[68:69], v[156:157], v[176:177]
	v_pk_fma_f32 v[156:157], v[64:65], v[156:157], v[158:159]
	s_waitcnt vmcnt(13)
	v_cndmask_b32_e64 v158, 0, v154, s[12:13]
	v_cndmask_b32_e64 v159, 0, v155, s[12:13]
	v_pk_fma_f32 v[166:167], v[78:79], v[162:163], v[166:167]
	v_pk_fma_f32 v[174:175], v[70:71], v[162:163], v[174:175]
	v_pk_fma_f32 v[160:161], v[66:67], v[162:163], v[160:161]
	v_lshlrev_b32_e32 v154, 16, v158
	v_and_b32_e32 v155, 0xffff0000, v158
	v_lshlrev_b32_e32 v158, 16, v159
	v_and_b32_e32 v159, 0xffff0000, v159
	v_pk_fma_f32 v[162:163], v[82:83], v[158:159], v[166:167]
	v_pk_fma_f32 v[164:165], v[80:81], v[154:155], v[164:165]
	v_pk_fma_f32 v[166:167], v[76:77], v[154:155], v[170:171]
	v_pk_fma_f32 v[168:169], v[78:79], v[158:159], v[168:169]
	v_pk_fma_f32 v[170:171], v[74:75], v[158:159], v[174:175]
	v_pk_fma_f32 v[172:173], v[72:73], v[154:155], v[172:173]
	v_pk_fma_f32 v[154:155], v[68:69], v[154:155], v[156:157]
	v_pk_fma_f32 v[156:157], v[70:71], v[158:159], v[160:161]
	s_waitcnt vmcnt(12)
	v_cndmask_b32_e64 v158, 0, v152, s[10:11]
	v_cndmask_b32_e64 v159, 0, v153, s[10:11]
	v_lshlrev_b32_e32 v152, 16, v158
	v_and_b32_e32 v153, 0xffff0000, v158
	v_lshlrev_b32_e32 v158, 16, v159
	v_and_b32_e32 v159, 0xffff0000, v159
	v_pk_fma_f32 v[160:161], v[84:85], v[152:153], v[164:165]
	v_pk_fma_f32 v[164:165], v[82:83], v[158:159], v[168:169]
	v_pk_fma_f32 v[166:167], v[80:81], v[152:153], v[166:167]
	v_pk_fma_f32 v[168:169], v[76:77], v[152:153], v[172:173]
	v_pk_fma_f32 v[152:153], v[72:73], v[152:153], v[154:155]
	s_waitcnt vmcnt(11)
	v_cndmask_b32_e64 v154, 0, v150, s[8:9]
	v_cndmask_b32_e64 v155, 0, v151, s[8:9]
	v_pk_fma_f32 v[162:163], v[86:87], v[158:159], v[162:163]
	v_pk_fma_f32 v[170:171], v[78:79], v[158:159], v[170:171]
	v_pk_fma_f32 v[156:157], v[74:75], v[158:159], v[156:157]
	v_lshlrev_b32_e32 v150, 16, v154
	v_and_b32_e32 v151, 0xffff0000, v154
	v_lshlrev_b32_e32 v154, 16, v155
	v_and_b32_e32 v155, 0xffff0000, v155
	v_pk_fma_f32 v[158:159], v[90:91], v[154:155], v[162:163]
	v_pk_fma_f32 v[160:161], v[88:89], v[150:151], v[160:161]
	v_pk_fma_f32 v[162:163], v[84:85], v[150:151], v[166:167]
	v_pk_fma_f32 v[164:165], v[86:87], v[154:155], v[164:165]
	v_pk_fma_f32 v[166:167], v[82:83], v[154:155], v[170:171]
	v_pk_fma_f32 v[168:169], v[80:81], v[150:151], v[168:169]
	v_pk_fma_f32 v[150:151], v[76:77], v[150:151], v[152:153]
	v_pk_fma_f32 v[152:153], v[78:79], v[154:155], v[156:157]
	s_waitcnt vmcnt(10)
	v_cndmask_b32_e64 v154, 0, v148, s[6:7]
	v_cndmask_b32_e64 v155, 0, v149, s[6:7]
	v_lshlrev_b32_e32 v148, 16, v154
	v_and_b32_e32 v149, 0xffff0000, v154
	v_lshlrev_b32_e32 v154, 16, v155
	v_and_b32_e32 v155, 0xffff0000, v155
	v_pk_fma_f32 v[156:157], v[92:93], v[148:149], v[160:161]
	v_pk_fma_f32 v[160:161], v[90:91], v[154:155], v[164:165]
	v_pk_fma_f32 v[162:163], v[88:89], v[148:149], v[162:163]
	v_pk_fma_f32 v[164:165], v[84:85], v[148:149], v[168:169]
	v_pk_fma_f32 v[148:149], v[80:81], v[148:149], v[150:151]
	s_waitcnt vmcnt(9)
	v_cndmask_b32_e64 v150, 0, v146, s[4:5]
	v_cndmask_b32_e64 v151, 0, v147, s[4:5]
	v_pk_fma_f32 v[158:159], v[94:95], v[154:155], v[158:159]
	v_pk_fma_f32 v[166:167], v[86:87], v[154:155], v[166:167]
	v_pk_fma_f32 v[152:153], v[82:83], v[154:155], v[152:153]
	v_lshlrev_b32_e32 v146, 16, v150
	v_and_b32_e32 v147, 0xffff0000, v150
	v_lshlrev_b32_e32 v150, 16, v151
	v_and_b32_e32 v151, 0xffff0000, v151
	v_pk_fma_f32 v[154:155], v[98:99], v[150:151], v[158:159]
	v_pk_fma_f32 v[156:157], v[96:97], v[146:147], v[156:157]
	v_pk_fma_f32 v[158:159], v[92:93], v[146:147], v[162:163]
	v_pk_fma_f32 v[160:161], v[94:95], v[150:151], v[160:161]
	v_pk_fma_f32 v[162:163], v[90:91], v[150:151], v[166:167]
	v_pk_fma_f32 v[164:165], v[88:89], v[146:147], v[164:165]
	v_pk_fma_f32 v[146:147], v[84:85], v[146:147], v[148:149]
	v_pk_fma_f32 v[148:149], v[86:87], v[150:151], v[152:153]
	s_waitcnt vmcnt(8)
	v_cndmask_b32_e64 v150, 0, v144, s[0:1]
	v_cndmask_b32_e64 v151, 0, v145, s[0:1]
	v_lshlrev_b32_e32 v144, 16, v150
	v_and_b32_e32 v145, 0xffff0000, v150
	v_lshlrev_b32_e32 v150, 16, v151
	v_and_b32_e32 v151, 0xffff0000, v151
	v_pk_fma_f32 v[152:153], v[100:101], v[144:145], v[156:157]
	v_pk_fma_f32 v[154:155], v[102:103], v[150:151], v[154:155]
	v_pk_fma_f32 v[156:157], v[98:99], v[150:151], v[160:161]
	v_pk_fma_f32 v[158:159], v[96:97], v[144:145], v[158:159]
	v_pk_fma_f32 v[160:161], v[92:93], v[144:145], v[164:165]
	v_pk_fma_f32 v[162:163], v[94:95], v[150:151], v[162:163]
	v_pk_fma_f32 v[148:149], v[90:91], v[150:151], v[148:149]
	v_pk_fma_f32 v[144:145], v[88:89], v[144:145], v[146:147]
	s_waitcnt vmcnt(7)
; DI float bf_lo(unsigned u) { return __uint_as_float(u << 16); }
; DI float bf_hi(unsigned u) { return __uint_as_float(u & 0xffff0000u); }
; DI void conv_unit(int item, const bf16_t* __restrict__ P, bf16_t* __restrict__ Y, const float* __restrict__ cw, const float* __restrict__ cb,
;                   const float* __restrict__ lng, const float* __restrict__ lnb, int lane) {
;     ...
;         for (int tt = 0; tt < 4; ++tt) { acc[tt] = bias;
; #pragma unroll
;             for (int j = 0; j < 31; ++j) { const u32x2 v = r[tt + j]; f32x4 x; x[0] = bf_lo(v.x); x[1] = bf_hi(v.x); x[2] = bf_lo(v.y); x[3] = bf_hi(v.y); acc[tt] += w[j] * x; } }
;         float mean[4], var[4];
; #pragma unroll
;         for (int tt = 0; tt < 4; ++tt) mean[tt] = (acc[tt][0] + acc[tt][1]) + (acc[tt][2] + acc[tt][3]);
; #pragma unroll
;         for (int o = 1; o < 64; o <<= 1) {
; #pragma unroll
;             for (int tt = 0; tt < 4; ++tt) mean[tt] += __shfl_xor(mean[tt], o); }
	v_cndmask_b32_e64 v147, v200, 0, s[66:67]
	v_cndmask_b32_e64 v151, v201, 0, s[66:67]
	s_waitcnt vmcnt(6)
	v_cndmask_b32_e64 v165, v198, 0, s[66:67]
	v_cndmask_b32_e64 v167, v199, 0, s[66:67]
	v_lshlrev_b32_e32 v146, 16, v147
	v_and_b32_e32 v147, 0xffff0000, v147
	v_lshlrev_b32_e32 v150, 16, v151
	v_and_b32_e32 v151, 0xffff0000, v151
	s_waitcnt vmcnt(5)
	v_cndmask_b32_e64 v168, v202, 0, s[66:67]
	v_cndmask_b32_e64 v169, v203, 0, s[66:67]
	v_pk_fma_f32 v[154:155], v[106:107], v[150:151], v[154:155]
	v_pk_fma_f32 v[152:153], v[104:105], v[146:147], v[152:153]
	v_lshlrev_b32_e32 v164, 16, v165
	v_and_b32_e32 v165, 0xffff0000, v165
	v_lshlrev_b32_e32 v166, 16, v167
	v_and_b32_e32 v167, 0xffff0000, v167
	v_pk_fma_f32 v[158:159], v[100:101], v[146:147], v[158:159]
	v_pk_fma_f32 v[156:157], v[102:103], v[150:151], v[156:157]
	v_pk_fma_f32 v[162:163], v[98:99], v[150:151], v[162:163]
	v_pk_fma_f32 v[160:161], v[96:97], v[146:147], v[160:161]
	v_pk_fma_f32 v[144:145], v[92:93], v[146:147], v[144:145]
	v_pk_fma_f32 v[146:147], v[94:95], v[150:151], v[148:149]
	s_waitcnt vmcnt(4)
	v_cndmask_b32_e64 v170, v204, 0, s[66:67]
	v_cndmask_b32_e64 v171, v205, 0, s[66:67]
	v_pk_fma_f32 v[148:149], v[108:109], v[164:165], v[152:153]
	v_pk_fma_f32 v[150:151], v[110:111], v[166:167], v[154:155]
	v_lshlrev_b32_e32 v152, 16, v168
	v_and_b32_e32 v153, 0xffff0000, v168
	v_lshlrev_b32_e32 v154, 16, v169
	v_and_b32_e32 v155, 0xffff0000, v169
	v_pk_fma_f32 v[156:157], v[106:107], v[166:167], v[156:157]
	v_pk_fma_f32 v[158:159], v[104:105], v[164:165], v[158:159]
	v_pk_fma_f32 v[160:161], v[100:101], v[164:165], v[160:161]
	v_pk_fma_f32 v[162:163], v[102:103], v[166:167], v[162:163]
	v_pk_fma_f32 v[146:147], v[98:99], v[166:167], v[146:147]
	v_pk_fma_f32 v[144:145], v[96:97], v[164:165], v[144:145]
	v_pk_fma_f32 v[150:151], v[114:115], v[154:155], v[150:151]
	v_pk_fma_f32 v[148:149], v[112:113], v[152:153], v[148:149]
	v_lshlrev_b32_e32 v164, 16, v170
	v_and_b32_e32 v165, 0xffff0000, v170
	v_lshlrev_b32_e32 v166, 16, v171
	v_and_b32_e32 v167, 0xffff0000, v171
	v_pk_fma_f32 v[158:159], v[108:109], v[152:153], v[158:159]
	v_pk_fma_f32 v[156:157], v[110:111], v[154:155], v[156:157]
	v_pk_fma_f32 v[162:163], v[106:107], v[154:155], v[162:163]
	v_pk_fma_f32 v[160:161], v[104:105], v[152:153], v[160:161]
	v_pk_fma_f32 v[144:145], v[100:101], v[152:153], v[144:145]
	v_pk_fma_f32 v[146:147], v[102:103], v[154:155], v[146:147]
	s_waitcnt vmcnt(3)
	v_lshlrev_b32_e32 v168, 16, v196
	v_and_b32_e32 v169, 0xffff0000, v196
	v_lshlrev_b32_e32 v170, 16, v197
	v_and_b32_e32 v171, 0xffff0000, v197
	v_pk_fma_f32 v[148:149], v[116:117], v[164:165], v[148:149]
	v_pk_fma_f32 v[150:151], v[118:119], v[166:167], v[150:151]
	v_pk_fma_f32 v[152:153], v[114:115], v[166:167], v[156:157]
	v_pk_fma_f32 v[154:155], v[112:113], v[164:165], v[158:159]
	v_pk_fma_f32 v[160:161], v[108:109], v[164:165], v[160:161]
	v_pk_fma_f32 v[162:163], v[110:111], v[166:167], v[162:163]
	v_pk_fma_f32 v[166:167], v[106:107], v[166:167], v[146:147]
	v_pk_fma_f32 v[164:165], v[104:105], v[164:165], v[144:145]
	s_waitcnt vmcnt(2)
	v_lshlrev_b32_e32 v156, 16, v194
	v_and_b32_e32 v157, 0xffff0000, v194
	v_lshlrev_b32_e32 v158, 16, v195
	v_and_b32_e32 v159, 0xffff0000, v195
	v_pk_fma_f32 v[144:145], v[122:123], v[170:171], v[150:151]
	v_pk_fma_f32 v[146:147], v[120:121], v[168:169], v[148:149]
	v_pk_fma_f32 v[148:149], v[116:117], v[168:169], v[154:155]
	v_pk_fma_f32 v[150:151], v[118:119], v[170:171], v[152:153]
	v_pk_fma_f32 v[152:153], v[114:115], v[170:171], v[162:163]
	v_pk_fma_f32 v[160:161], v[112:113], v[168:169], v[160:161]
	v_pk_fma_f32 v[164:165], v[108:109], v[168:169], v[164:165]
	v_pk_fma_f32 v[166:167], v[110:111], v[170:171], v[166:167]
	s_waitcnt vmcnt(1)
	v_lshlrev_b32_e32 v162, 16, v192
	v_and_b32_e32 v163, 0xffff0000, v192
	v_lshlrev_b32_e32 v172, 16, v193
	v_and_b32_e32 v173, 0xffff0000, v193
	v_pk_fma_f32 v[150:151], v[122:123], v[158:159], v[150:151]
	v_pk_fma_f32 v[154:155], v[120:121], v[156:157], v[148:149]
	v_pk_fma_f32 v[148:149], v[116:117], v[156:157], v[160:161]
	v_pk_fma_f32 v[152:153], v[118:119], v[158:159], v[152:153]
	v_pk_fma_f32 v[158:159], v[114:115], v[158:159], v[166:167]
	v_pk_fma_f32 v[160:161], v[112:113], v[156:157], v[164:165]
	v_pk_mov_b32 v[166:167], v[146:147], v[144:145] op_sel:[1,0]
	v_mov_b32_e32 v168, v146
	v_mov_b32_e32 v169, v145
	s_waitcnt vmcnt(0)
	v_lshlrev_b32_e32 v164, 16, v138
	v_and_b32_e32 v165, 0xffff0000, v138
	v_lshlrev_b32_e32 v138, 16, v139
	v_and_b32_e32 v139, 0xffff0000, v139
	v_pk_fma_f32 v[152:153], v[122:123], v[172:173], v[152:153]
	v_pk_fma_f32 v[156:157], v[120:121], v[162:163], v[148:149]
	v_pk_fma_f32 v[148:149], v[116:117], v[162:163], v[160:161]
	v_pk_fma_f32 v[158:159], v[118:119], v[172:173], v[158:159]
	v_pk_add_f32 v[160:161], v[166:167], v[168:169]
	v_pk_mov_b32 v[162:163], v[154:155], v[150:151] op_sel:[1,0]
	v_mov_b32_e32 v166, v154
	v_mov_b32_e32 v167, v151
	v_pk_fma_f32 v[138:139], v[122:123], v[138:139], v[158:159]
	v_pk_fma_f32 v[148:149], v[120:121], v[164:165], v[148:149]
	v_add_f32_e32 v164, v160, v161
	v_pk_add_f32 v[158:159], v[162:163], v[166:167]
	v_pk_mov_b32 v[160:161], v[156:157], v[152:153] op_sel:[1,0]
	v_mov_b32_e32 v162, v156
	v_mov_b32_e32 v163, v153
	v_add_f32_e32 v165, v158, v159
	v_pk_add_f32 v[158:159], v[160:161], v[162:163]
	v_pk_mov_b32 v[160:161], v[148:149], v[138:139] op_sel:[1,0]
	v_mov_b32_e32 v162, v148
	v_mov_b32_e32 v163, v139
	ds_bpermute_b32 v166, v206, v164
	v_add_f32_e32 v167, v158, v159
	v_pk_add_f32 v[158:159], v[160:161], v[162:163]
	ds_bpermute_b32 v160, v206, v165
	v_add_f32_e32 v158, v158, v159
	ds_bpermute_b32 v159, v206, v167
	ds_bpermute_b32 v161, v206, v158
	s_waitcnt lgkmcnt(3)
; DI void conv_unit(int item, const bf16_t* __restrict__ P, bf16_t* __restrict__ Y, const float* __restrict__ cw, const float* __restrict__ cb,
;                   const float* __restrict__ lng, const float* __restrict__ lnb, int lane) {
;     ...
;         for (int o = 1; o < 64; o <<= 1) {
; #pragma unroll
;             for (int tt = 0; tt < 4; ++tt) mean[tt] += __shfl_xor(mean[tt], o); }
; #pragma unroll
;         for (int tt = 0; tt < 4; ++tt) { mean[tt] *= (1.0f / 256.0f); acc[tt] -= mean[tt]; var[tt] = (acc[tt][0] * acc[tt][0] + acc[tt][1] * acc[tt][1]) + (acc[tt][2] * acc[tt][2] + acc[tt][3] * acc[tt][3]); }
; #pragma unroll
;         for (int o = 1; o < 64; o <<= 1) {
; #pragma unroll
;             for (int tt = 0; tt < 4; ++tt) var[tt] += __shfl_xor(var[tt], o); }
; #pragma unroll
;         for (int tt = 0; tt < 4; ++tt) {
;             const float rs = 1.0f / sqrtf(var[tt] * (1.0f / 256.0f) + 1e-6f);
	v_add_f32_e32 v162, v164, v166
	s_waitcnt lgkmcnt(2)
	v_add_f32_e32 v160, v165, v160
	ds_bpermute_b32 v163, v207, v162
	s_waitcnt lgkmcnt(2)
	v_add_f32_e32 v159, v167, v159
	ds_bpermute_b32 v164, v207, v160
	s_waitcnt lgkmcnt(2)
	v_add_f32_e32 v158, v158, v161
	ds_bpermute_b32 v161, v207, v159
	ds_bpermute_b32 v165, v207, v158
	s_waitcnt lgkmcnt(3)
	v_add_f32_e32 v162, v162, v163
	s_waitcnt lgkmcnt(2)
	v_add_f32_e32 v160, v160, v164
	ds_bpermute_b32 v163, v208, v162
	s_waitcnt lgkmcnt(2)
	v_add_f32_e32 v159, v159, v161
	ds_bpermute_b32 v161, v208, v160
	s_waitcnt lgkmcnt(2)
	v_add_f32_e32 v158, v158, v165
	ds_bpermute_b32 v164, v208, v159
	ds_bpermute_b32 v165, v208, v158
	s_waitcnt lgkmcnt(3)
	v_add_f32_e32 v162, v162, v163
	s_waitcnt lgkmcnt(2)
	v_add_f32_e32 v160, v160, v161
	ds_bpermute_b32 v161, v209, v162
	s_waitcnt lgkmcnt(2)
	v_add_f32_e32 v159, v159, v164
	ds_bpermute_b32 v163, v209, v160
	s_waitcnt lgkmcnt(2)
	v_add_f32_e32 v158, v158, v165
	ds_bpermute_b32 v164, v209, v159
	ds_bpermute_b32 v165, v209, v158
	s_waitcnt lgkmcnt(3)
	v_add_f32_e32 v161, v162, v161
	s_waitcnt lgkmcnt(2)
	v_add_f32_e32 v160, v160, v163
	ds_bpermute_b32 v162, v210, v161
	s_waitcnt lgkmcnt(2)
	v_add_f32_e32 v159, v159, v164
	ds_bpermute_b32 v163, v210, v160
	s_waitcnt lgkmcnt(2)
	v_add_f32_e32 v158, v158, v165
	ds_bpermute_b32 v164, v210, v159
	ds_bpermute_b32 v165, v210, v158
	s_waitcnt lgkmcnt(3)
	v_add_f32_e32 v161, v161, v162
	s_waitcnt lgkmcnt(2)
	v_add_f32_e32 v160, v160, v163
	ds_bpermute_b32 v162, v211, v161
	s_waitcnt lgkmcnt(2)
	v_add_f32_e32 v159, v159, v164
	ds_bpermute_b32 v163, v211, v160
	s_waitcnt lgkmcnt(2)
	v_add_f32_e32 v164, v158, v165
	ds_bpermute_b32 v158, v211, v159
	ds_bpermute_b32 v165, v211, v164
	s_waitcnt lgkmcnt(3)
	v_add_f32_e32 v161, v161, v162
	s_waitcnt lgkmcnt(2)
	v_add_f32_e32 v162, v160, v163
	v_fmamk_f32 v147, v161, 0xbb800000, v147
	v_fmac_f32_e32 v146, 0xbb800000, v161
	v_fmamk_f32 v145, v161, 0xbb800000, v145
	v_fmac_f32_e32 v144, 0xbb800000, v161
	s_waitcnt lgkmcnt(1)
	v_add_f32_e32 v166, v159, v158
	v_pk_mul_f32 v[158:159], v[144:145], v[144:145]
	v_pk_mul_f32 v[160:161], v[146:147], v[146:147]
	v_fmamk_f32 v155, v162, 0xbb800000, v155
	v_fmac_f32_e32 v154, 0xbb800000, v162
	v_fmamk_f32 v151, v162, 0xbb800000, v151
	v_fmac_f32_e32 v150, 0xbb800000, v162
	s_waitcnt lgkmcnt(0)
	v_add_f32_e32 v168, v164, v165
	v_pk_mov_b32 v[162:163], v[160:161], v[158:159] op_sel:[1,0]
	v_mov_b32_e32 v161, v159
	v_pk_mul_f32 v[158:159], v[150:151], v[150:151]
	v_pk_mul_f32 v[164:165], v[154:155], v[154:155]
	v_fmamk_f32 v157, v166, 0xbb800000, v157
	v_fmac_f32_e32 v156, 0xbb800000, v166
	v_fmamk_f32 v153, v166, 0xbb800000, v153
	v_fmac_f32_e32 v152, 0xbb800000, v166
	v_pk_add_f32 v[160:161], v[162:163], v[160:161]
	v_pk_mov_b32 v[162:163], v[164:165], v[158:159] op_sel:[1,0]
	v_mov_b32_e32 v165, v159
	v_pk_mul_f32 v[158:159], v[152:153], v[152:153]
	v_pk_mul_f32 v[166:167], v[156:157], v[156:157]
	v_fmamk_f32 v149, v168, 0xbb800000, v149
	v_fmac_f32_e32 v148, 0xbb800000, v168
	v_fmamk_f32 v139, v168, 0xbb800000, v139
	v_fmac_f32_e32 v138, 0xbb800000, v168
	v_add_f32_e32 v168, v160, v161
	v_pk_add_f32 v[160:161], v[162:163], v[164:165]
	v_pk_mov_b32 v[162:163], v[166:167], v[158:159] op_sel:[1,0]
	v_mov_b32_e32 v167, v159
	v_pk_mul_f32 v[158:159], v[138:139], v[138:139]
	v_pk_mul_f32 v[164:165], v[148:149], v[148:149]
	v_add_f32_e32 v169, v160, v161
	v_pk_add_f32 v[160:161], v[162:163], v[166:167]
	v_pk_mov_b32 v[162:163], v[164:165], v[158:159] op_sel:[1,0]
	v_mov_b32_e32 v165, v159
	ds_bpermute_b32 v166, v206, v168
	v_add_f32_e32 v160, v160, v161
	v_pk_add_f32 v[158:159], v[162:163], v[164:165]
	ds_bpermute_b32 v161, v206, v169
	v_add_f32_e32 v158, v158, v159
	ds_bpermute_b32 v159, v206, v160
	ds_bpermute_b32 v162, v206, v158
	s_waitcnt lgkmcnt(3)
	v_add_f32_e32 v163, v168, v166
	s_waitcnt lgkmcnt(2)
	v_add_f32_e32 v161, v169, v161
	ds_bpermute_b32 v164, v207, v163
	s_waitcnt lgkmcnt(2)
	v_add_f32_e32 v159, v160, v159
	ds_bpermute_b32 v160, v207, v161
	s_waitcnt lgkmcnt(2)
	v_add_f32_e32 v158, v158, v162
	ds_bpermute_b32 v162, v207, v159
	s_waitcnt lgkmcnt(2)
	v_add_f32_e32 v163, v163, v164
	ds_bpermute_b32 v165, v207, v158
	s_waitcnt lgkmcnt(2)
	v_add_f32_e32 v160, v161, v160
	ds_bpermute_b32 v161, v208, v163
	s_waitcnt lgkmcnt(2)
	v_add_f32_e32 v159, v159, v162
	ds_bpermute_b32 v162, v208, v160
	ds_bpermute_b32 v164, v208, v159
	s_waitcnt lgkmcnt(3)
	v_add_f32_e32 v158, v158, v165
	s_waitcnt lgkmcnt(2)
	v_add_f32_e32 v161, v163, v161
	ds_bpermute_b32 v165, v208, v158
	s_waitcnt lgkmcnt(2)
	v_add_f32_e32 v160, v160, v162
	ds_bpermute_b32 v162, v209, v161
	ds_bpermute_b32 v163, v209, v160
	s_waitcnt lgkmcnt(3)
	v_add_f32_e32 v159, v159, v164
	ds_bpermute_b32 v164, v209, v159
	s_waitcnt lgkmcnt(3)
	v_add_f32_e32 v158, v158, v165
	s_waitcnt lgkmcnt(2)
	v_add_f32_e32 v161, v161, v162
	ds_bpermute_b32 v165, v209, v158
	ds_bpermute_b32 v162, v210, v161
	s_waitcnt lgkmcnt(3)
	v_add_f32_e32 v160, v160, v163
	ds_bpermute_b32 v163, v210, v160
	s_waitcnt lgkmcnt(3)
	v_add_f32_e32 v159, v159, v164
	ds_bpermute_b32 v164, v210, v159
	s_waitcnt lgkmcnt(3)
	v_add_f32_e32 v158, v158, v165
	s_waitcnt lgkmcnt(2)
	v_add_f32_e32 v161, v161, v162
	ds_bpermute_b32 v165, v210, v158
	ds_bpermute_b32 v162, v211, v161
	s_waitcnt lgkmcnt(3)
	v_add_f32_e32 v160, v160, v163
	ds_bpermute_b32 v163, v211, v160
	s_waitcnt lgkmcnt(3)
	v_add_f32_e32 v159, v159, v164
	ds_bpermute_b32 v164, v211, v159
	s_waitcnt lgkmcnt(3)
	v_add_f32_e32 v158, v158, v165
	s_waitcnt lgkmcnt(2)
	v_add_f32_e32 v161, v161, v162
	ds_bpermute_b32 v165, v211, v158
	v_fmamk_f32 v161, v161, 0x3b800000, v212
	s_waitcnt lgkmcnt(2)
; DI void conv_unit(int item, const bf16_t* __restrict__ P, bf16_t* __restrict__ Y, const float* __restrict__ cw, const float* __restrict__ cb,
;                   const float* __restrict__ lng, const float* __restrict__ lnb, int lane) {
;     ...
;             const float rs = 1.0f / sqrtf(var[tt] * (1.0f / 256.0f) + 1e-6f);
	v_add_f32_e32 v160, v160, v163
	v_mul_f32_e32 v162, 0x4f800000, v161
	v_cmp_gt_f32_e32 vcc, s62, v161
	v_fmamk_f32 v160, v160, 0x3b800000, v212
	s_waitcnt lgkmcnt(1)
	v_add_f32_e32 v159, v159, v164
	v_cndmask_b32_e32 v161, v161, v162, vcc
	v_mul_f32_e32 v162, 0x4f800000, v160
	v_cmp_gt_f32_e64 s[0:1], s62, v160
	v_sqrt_f32_e32 v163, v161
	v_fmamk_f32 v159, v159, 0x3b800000, v212
	v_cndmask_b32_e64 v160, v160, v162, s[0:1]
	s_waitcnt lgkmcnt(0)
	v_add_f32_e32 v158, v158, v165
	v_mul_f32_e32 v162, 0x4f800000, v159
	v_cmp_gt_f32_e64 s[4:5], s62, v159
	v_sqrt_f32_e32 v164, v160
	v_fmamk_f32 v158, v158, 0x3b800000, v212
	v_cndmask_b32_e64 v159, v159, v162, s[4:5]
	v_mul_f32_e32 v162, 0x4f800000, v158
	v_cmp_gt_f32_e64 s[6:7], s62, v158
	v_sqrt_f32_e32 v165, v159
	v_add_u32_e32 v166, -1, v163
	v_cndmask_b32_e64 v158, v158, v162, s[6:7]
	v_add_u32_e32 v167, 1, v163
	v_fma_f32 v168, -v166, v163, v161
	v_sqrt_f32_e32 v162, v158
	v_fma_f32 v169, -v167, v163, v161
	v_add_u32_e32 v170, -1, v164
	v_cmp_ge_f32_e64 s[8:9], 0, v168
	v_add_u32_e32 v171, 1, v164
	v_fma_f32 v168, -v171, v164, v160
	v_cndmask_b32_e64 v163, v163, v166, s[8:9]
	v_fma_f32 v166, -v170, v164, v160
	v_cmp_lt_f32_e64 s[8:9], 0, v169
	v_add_u32_e32 v172, -1, v165
	v_add_u32_e32 v173, 1, v165
	v_cndmask_b32_e64 v163, v163, v167, s[8:9]
	v_cmp_ge_f32_e64 s[8:9], 0, v166
	v_fma_f32 v166, -v172, v165, v159
	v_fma_f32 v167, -v173, v165, v159
	v_cndmask_b32_e64 v164, v164, v170, s[8:9]
	v_cmp_lt_f32_e64 s[8:9], 0, v168
	v_add_u32_e32 v168, -1, v162
	v_add_u32_e32 v169, 1, v162
	v_cndmask_b32_e64 v164, v164, v171, s[8:9]
	v_cmp_ge_f32_e64 s[8:9], 0, v166
	v_mul_f32_e32 v170, 0x37800000, v163
	v_fma_f32 v166, -v168, v162, v158
	v_cndmask_b32_e64 v165, v165, v172, s[8:9]
	v_cmp_lt_f32_e64 s[8:9], 0, v167
	v_fma_f32 v167, -v169, v162, v158
	v_cndmask_b32_e32 v163, v163, v170, vcc
	v_cndmask_b32_e64 v165, v165, v173, s[8:9]
	v_cmp_ge_f32_e32 vcc, 0, v166
	v_cmp_class_f32_e64 s[8:9], v161, v213
	v_mul_f32_e32 v170, 0x37800000, v164
	v_cndmask_b32_e32 v162, v162, v168, vcc
	v_cmp_lt_f32_e32 vcc, 0, v167
	v_cndmask_b32_e64 v161, v163, v161, s[8:9]
	v_cndmask_b32_e64 v163, v164, v170, s[0:1]
	v_cmp_class_f32_e64 s[0:1], v160, v213
	v_mul_f32_e32 v164, 0x37800000, v165
	v_cndmask_b32_e32 v162, v162, v169, vcc
	v_div_scale_f32 v166, s[8:9], v161, v161, 1.0
	v_cndmask_b32_e64 v160, v163, v160, s[0:1]
	v_cndmask_b32_e64 v163, v165, v164, s[4:5]
	v_cmp_class_f32_e64 s[0:1], v159, v213
	v_mul_f32_e32 v164, 0x37800000, v162
	v_rcp_f32_e32 v165, v166
	v_div_scale_f32 v168, s[4:5], v160, v160, 1.0
	v_cndmask_b32_e64 v159, v163, v159, s[0:1]
	v_cndmask_b32_e64 v162, v162, v164, s[6:7]
	v_cmp_class_f32_e64 s[0:1], v158, v213
	v_rcp_f32_e32 v163, v168
	v_div_scale_f32 v164, s[6:7], v159, v159, 1.0
	v_cndmask_b32_e64 v162, v162, v158, s[0:1]
	v_rcp_f32_e32 v171, v164
	v_div_scale_f32 v172, s[0:1], v162, v162, 1.0
	v_rcp_f32_e32 v174, v172
	v_fma_f32 v158, -v166, v165, 1.0
	v_div_scale_f32 v167, vcc, 1.0, v161, 1.0
	v_fmac_f32_e32 v165, v158, v165
	v_fma_f32 v158, -v168, v163, 1.0
	v_mul_f32_e32 v175, v167, v165
	v_div_scale_f32 v169, s[4:5], 1.0, v160, 1.0
	v_fmac_f32_e32 v163, v158, v163
	v_fma_f32 v158, -v164, v171, 1.0
	v_fma_f32 v176, -v166, v175, v167
	v_div_scale_f32 v170, s[6:7], 1.0, v159, 1.0
	v_mul_f32_e32 v177, v169, v163
	v_fmac_f32_e32 v171, v158, v171
	v_fma_f32 v158, -v172, v174, 1.0
	v_fmac_f32_e32 v175, v176, v165
	v_div_scale_f32 v173, s[0:1], 1.0, v162, 1.0
	v_fma_f32 v176, -v168, v177, v169
	v_mul_f32_e32 v178, v170, v171
	v_fmac_f32_e32 v174, v158, v174
	v_fma_f32 v158, -v166, v175, v167
	v_fmac_f32_e32 v177, v176, v163
	v_fma_f32 v166, -v164, v178, v170
	v_mul_f32_e32 v167, v173, v174
	v_div_fmas_f32 v158, v158, v165, v175
	v_fma_f32 v165, -v168, v177, v169
	v_fmac_f32_e32 v178, v166, v171
	v_fma_f32 v166, -v172, v167, v173
	v_div_fixup_f32 v158, v158, v161, 1.0
	s_mov_b64 vcc, s[4:5]
	v_div_fmas_f32 v161, v165, v163, v177
	v_fma_f32 v163, -v164, v178, v170
	v_fmac_f32_e32 v167, v166, v174
	v_pk_mul_f32 v[146:147], v[146:147], v[158:159] op_sel_hi:[1,0]
	s_mov_b64 vcc, s[6:7]
	v_pk_mul_f32 v[144:145], v[144:145], v[158:159] op_sel_hi:[1,0]
	v_div_fixup_f32 v158, v161, v160, 1.0
	v_div_fmas_f32 v160, v163, v171, v178
; __device__ __forceinline__ f32x4 silu4(const f32x4 g) { f32x4 o; o[0] = g[0] * sigmoid_f(g[0]); o[1] = g[1] * sigmoid_f(g[1]); o[2] = g[2] * sigmoid_f(g[2]); o[3] = g[3] * sigmoid_f(g[3]); return o; }
; DI void conv_unit(int item, const bf16_t* __restrict__ P, bf16_t* __restrict__ Y, const float* __restrict__ cw, const float* __restrict__ cb,
;                   const float* __restrict__ lng, const float* __restrict__ lnb, int lane) {
;     ...
;         for (int tt = 0; tt < 4; ++tt) {
;             const float rs = 1.0f / sqrtf(var[tt] * (1.0f / 256.0f) + 1e-6f);
;             const f32x4 y = pg8::silu4(acc[tt] * rs * g4 + b4);
;             u32x2 o; o.x = pk2(y[0], y[1]); o.y = pk2(y[2], y[3]);
;             *(u32x2*)(Y + (size_t)(tok + tt) * DM + Y_CV + 4 * lane) = o;
;         }
;     }
	v_fma_f32 v161, -v172, v167, v173
	v_pk_fma_f32 v[146:147], v[128:129], v[146:147], v[132:133]
	s_mov_b64 vcc, s[0:1]
	v_pk_mul_f32 v[154:155], v[154:155], v[158:159] op_sel_hi:[1,0]
	v_pk_mul_f32 v[150:151], v[150:151], v[158:159] op_sel_hi:[1,0]
	v_div_fixup_f32 v158, v160, v159, 1.0
	v_div_fmas_f32 v159, v161, v174, v167
	v_mul_f32_e32 v160, 0xbfb8aa3b, v146
	v_pk_mul_f32 v[156:157], v[156:157], v[158:159] op_sel_hi:[1,0]
	v_pk_mul_f32 v[152:153], v[152:153], v[158:159] op_sel_hi:[1,0]
	v_div_fixup_f32 v158, v159, v162, 1.0
	v_exp_f32_e32 v159, v160
	v_pk_fma_f32 v[144:145], v[130:131], v[144:145], v[134:135]
	v_mul_f32_e32 v161, 0xbfb8aa3b, v147
	v_mul_f32_e32 v163, 0xbfb8aa3b, v144
	v_mul_f32_e32 v164, 0xbfb8aa3b, v145
	v_pk_fma_f32 v[150:151], v[130:131], v[150:151], v[134:135]
	v_pk_fma_f32 v[154:155], v[128:129], v[154:155], v[132:133]
	v_exp_f32_e32 v160, v161
	v_exp_f32_e32 v161, v163
	v_exp_f32_e32 v162, v164
	v_mul_f32_e32 v163, 0xbfb8aa3b, v154
	v_mul_f32_e32 v164, 0xbfb8aa3b, v155
	v_mul_f32_e32 v165, 0xbfb8aa3b, v150
	v_mul_f32_e32 v166, 0xbfb8aa3b, v151
	v_pk_fma_f32 v[156:157], v[128:129], v[156:157], v[132:133]
	v_pk_mul_f32 v[148:149], v[148:149], v[158:159] op_sel_hi:[1,0]
	v_pk_mul_f32 v[138:139], v[138:139], v[158:159] op_sel_hi:[1,0]
	v_pk_fma_f32 v[152:153], v[130:131], v[152:153], v[134:135]
	v_exp_f32_e32 v158, v163
	v_exp_f32_e32 v163, v164
	v_exp_f32_e32 v164, v165
	v_exp_f32_e32 v165, v166
	v_mul_f32_e32 v166, 0xbfb8aa3b, v156
	v_mul_f32_e32 v167, 0xbfb8aa3b, v157
	v_pk_fma_f32 v[138:139], v[130:131], v[138:139], v[134:135]
	v_pk_fma_f32 v[148:149], v[128:129], v[148:149], v[132:133]
	v_mul_f32_e32 v168, 0xbfb8aa3b, v152
	v_mul_f32_e32 v169, 0xbfb8aa3b, v153
	v_exp_f32_e32 v166, v166
	v_exp_f32_e32 v167, v167
	v_mul_f32_e32 v170, 0xbfb8aa3b, v148
	v_mul_f32_e32 v171, 0xbfb8aa3b, v149
	v_mul_f32_e32 v172, 0xbfb8aa3b, v138
	v_mul_f32_e32 v173, 0xbfb8aa3b, v139
	v_exp_f32_e32 v168, v168
	v_exp_f32_e32 v169, v169
	v_exp_f32_e32 v170, v170
	v_exp_f32_e32 v171, v171
	v_exp_f32_e32 v172, v172
	v_exp_f32_e32 v173, v173
	v_add_f32_e32 v159, 1.0, v159
	v_add_f32_e32 v160, 1.0, v160
	v_add_f32_e32 v161, 1.0, v161
	v_add_f32_e32 v162, 1.0, v162
	v_rcp_f32_e32 v159, v159
	v_rcp_f32_e32 v160, v160
	v_rcp_f32_e32 v161, v161
	v_rcp_f32_e32 v162, v162
	v_add_f32_e32 v158, 1.0, v158
	v_add_f32_e32 v163, 1.0, v163
	v_add_f32_e32 v164, 1.0, v164
	v_add_f32_e32 v165, 1.0, v165
	v_rcp_f32_e32 v158, v158
	v_rcp_f32_e32 v163, v163
	v_rcp_f32_e32 v164, v164
	v_rcp_f32_e32 v165, v165
	v_add_f32_e32 v166, 1.0, v166
	v_add_f32_e32 v167, 1.0, v167
	v_add_f32_e32 v168, 1.0, v168
	v_add_f32_e32 v169, 1.0, v169
	v_rcp_f32_e32 v166, v166
	v_rcp_f32_e32 v167, v167
	v_add_f32_e32 v170, 1.0, v170
	v_add_f32_e32 v171, 1.0, v171
	v_add_f32_e32 v172, 1.0, v172
	v_add_f32_e32 v173, 1.0, v173
	s_add_i32 s3, s3, 4
	v_rcp_f32_e32 v168, v168
	v_rcp_f32_e32 v169, v169
	v_rcp_f32_e32 v170, v170
	v_rcp_f32_e32 v171, v171
	v_rcp_f32_e32 v172, v172
	v_rcp_f32_e32 v173, v173
	s_add_u32 s58, s58, 0x2000
	v_mul_f32_e32 v146, v146, v159
	v_mul_f32_e32 v147, v147, v160
	v_mul_f32_e32 v159, v144, v161
	v_mul_f32_e32 v145, v145, v162
	s_addc_u32 s59, s59, 0
	v_cvt_pk_bf16_f32 v144, v146, v147
	v_cvt_pk_bf16_f32 v145, v159, v145
	v_mul_f32_e32 v146, v154, v158
	v_mul_f32_e32 v147, v155, v163
	v_mul_f32_e32 v150, v150, v164
	v_mul_f32_e32 v151, v151, v165
	s_add_u32 s64, s64, 0x4200
	global_store_dwordx2 v[140:141], v[144:145], off offset:-4096
	v_cvt_pk_bf16_f32 v144, v146, v147
	v_cvt_pk_bf16_f32 v145, v150, v151
	v_mul_f32_e32 v146, v156, v166
	v_mul_f32_e32 v147, v157, v167
	s_addc_u32 s65, s65, 0
	v_mul_f32_e32 v150, v152, v168
	v_mul_f32_e32 v151, v153, v169
	global_store_dwordx2 v[142:143], v[144:145], off offset:2048
	v_cvt_pk_bf16_f32 v142, v146, v147
	v_mul_f32_e32 v144, v148, v170
	v_mul_f32_e32 v145, v149, v171
	v_mul_f32_e32 v146, v138, v172
	v_mul_f32_e32 v139, v139, v173
	s_cmp_eq_u32 s3, s100
	v_cvt_pk_bf16_f32 v143, v150, v151
	v_cvt_pk_bf16_f32 v138, v144, v145
	v_cvt_pk_bf16_f32 v139, v146, v139
	global_store_dwordx2 v[140:141], v[142:143], off
	global_store_dwordx2 v[140:141], v[138:139], off offset:2048
	s_cbranch_scc0 .LBB0_1585
	s_mov_b64 s[46:47], s[72:73]

; #define LAS __attribute__((address_space(3)))
; #define PHASE(k) if (lo <= (k) && (k) < hi) { if ((k) > lo) SEAM(k); run_phase<(k)>(a, lds, lane, wave); if constexpr ((REP_MASK >> (k)) & 1) { xcd_barrier(bar); run_phase<(k), 1>(a, lds, lane, wave); } }
; __global__ void __launch_bounds__(NTHR, 2) mk_fwd(Args a) {
;     extern __shared__ __attribute__((aligned(16))) unsigned char lds_raw[];
;     LAS unsigned char* lds = (LAS unsigned char*)lds_raw;
;     cg::grid_group grid = cg::this_grid();
;     const int lane = threadIdx.x & 63, wave = __builtin_amdgcn_readfirstlane(threadIdx.x >> 6);
;     const int lo = a.ph_lo, hi = a.ph_hi;
;     volatile LAS unsigned* bst = (volatile LAS unsigned*)(lds + RS_OFF + RS_SLOTS * 1024);
;     if (threadIdx.x < 2) bst[threadIdx.x] = 0u;
;     __syncthreads();
;     XcdBarrier bar; bar.bar = (unsigned*)(a.ws + WS_CTL) + 4096; bar.x = 0; bar.st = bst;
;     if (hi - lo > 1) bar = xcd_barrier_post((unsigned*)(a.ws + WS_CTL) + 4096, bst);
;     ...
;     if (hi - lo > N_PHASES) grid.sync();
;     ...
;     PHASE(0)
;     ...
;     for (int i = 0; i < EXTRA_SYNCS; ++i) xcd_barrier(bar);
;     ...
;     PHASE(1) PHASE(2) PHASE(3) PHASE(4) PHASE(5) PHASE(6) PHASE(7) PHASE(8) PHASE(9) PHASE(10) PHASE(11) PHASE(12) PHASE(13) PHASE(14) PHASE(15) PHASE(16) PHASE(17) PHASE(18) PHASE(19)
;     ...
; }
	.amdhsa_kernel _Z6mk_fwd4Args
		.amdhsa_group_segment_fixed_size 0
		.amdhsa_private_segment_fixed_size 0
		.amdhsa_kernarg_size 408
		.amdhsa_user_sgpr_count 2
		.amdhsa_user_sgpr_dispatch_ptr 0
		.amdhsa_user_sgpr_queue_ptr 0
		.amdhsa_user_sgpr_kernarg_segment_ptr 1
		.amdhsa_user_sgpr_dispatch_id 0
		.amdhsa_user_sgpr_kernarg_preload_length 0
		.amdhsa_user_sgpr_kernarg_preload_offset 0
		.amdhsa_user_sgpr_private_segment_size 0
		.amdhsa_uses_dynamic_stack 0
		.amdhsa_enable_private_segment 0
		.amdhsa_system_sgpr_workgroup_id_x 1
		.amdhsa_system_sgpr_workgroup_id_y 0
		.amdhsa_system_sgpr_workgroup_id_z 0
		.amdhsa_system_sgpr_workgroup_info 0
		.amdhsa_system_vgpr_workitem_id 2
		.amdhsa_next_free_vgpr 256
		.amdhsa_next_free_sgpr 102
		.amdhsa_accum_offset 256
		.amdhsa_reserve_vcc 1
		.amdhsa_float_round_mode_32 0
		.amdhsa_float_round_mode_16_64 0
		.amdhsa_float_denorm_mode_32 3
		.amdhsa_float_denorm_mode_16_64 3
		.amdhsa_dx10_clamp 1
		.amdhsa_ieee_mode 1
		.amdhsa_fp16_overflow 0
		.amdhsa_tg_split 0
		.amdhsa_exception_fp_ieee_invalid_op 0
		.amdhsa_exception_fp_denorm_src 0
		.amdhsa_exception_fp_ieee_div_zero 0
		.amdhsa_exception_fp_ieee_overflow 0
		.amdhsa_exception_fp_ieee_underflow 0
		.amdhsa_exception_fp_ieee_inexact 0
		.amdhsa_exception_int_div_zero 0
	.end_amdhsa_kernel

; __global__ void __launch_bounds__(NTHR, 2) mk_fwd(Args a) {
amdhsa.kernels:
  - .agpr_count:     0
    .args:
      - .offset:         0
        .size:           152
        .value_kind:     by_value
      - .offset:         152
        .size:           4
        .value_kind:     hidden_block_count_x
      - .offset:         156
        .size:           4
        .value_kind:     hidden_block_count_y
      - .offset:         160
        .size:           4
        .value_kind:     hidden_block_count_z
      - .offset:         164
        .size:           2
        .value_kind:     hidden_group_size_x
      - .offset:         166
        .size:           2
        .value_kind:     hidden_group_size_y
      - .offset:         168
        .size:           2
        .value_kind:     hidden_group_size_z
      - .offset:         170
        .size:           2
        .value_kind:     hidden_remainder_x
      - .offset:         172
        .size:           2
        .value_kind:     hidden_remainder_y
      - .offset:         174
        .size:           2
        .value_kind:     hidden_remainder_z
      - .offset:         192
        .size:           8
        .value_kind:     hidden_global_offset_x
      - .offset:         200
        .size:           8
        .value_kind:     hidden_global_offset_y
      - .offset:         208
        .size:           8
        .value_kind:     hidden_global_offset_z
      - .offset:         216
        .size:           2
        .value_kind:     hidden_grid_dims
      - .offset:         240
        .size:           8
        .value_kind:     hidden_multigrid_sync_arg
      - .offset:         272
        .size:           4
        .value_kind:     hidden_dynamic_lds_size
    .group_segment_fixed_size: 0
    .kernarg_segment_align: 8
    .kernarg_segment_size: 408
    .language:       OpenCL C
    .language_version:
      - 2
      - 0
    .max_flat_workgroup_size: 512
    .name:           _Z6mk_fwd4Args
    .private_segment_fixed_size: 0
    .sgpr_count:     108
    .sgpr_spill_count: 27
    .symbol:         _Z6mk_fwd4Args.kd
    .uniform_work_group_size: 1
    .uses_dynamic_stack: false
    .vgpr_count:     256
    .vgpr_spill_count: 0
    .wavefront_size: 64
